# EPI_RESID epilogue de-serialised: 20 loads in flight per 32x32 block, pipelined across blocks, block-0 loads before acc conversion (P7/P16/FFN2)
# speedup vs baseline: 1.1323x; 1.0299x over previous
.LBB0_282:
	s_add_u32 m0, s100, 0x8000
	s_nop 0
	global_load_lds_dwordx4 v[134:135], off
	s_add_u32 m0, s100, 0x9000
	s_nop 0
	global_load_lds_dwordx4 v[152:153], off
	s_add_u32 m0, s100, 0xa000
	s_nop 0
	global_load_lds_dwordx4 v[154:155], off
	s_add_u32 m0, s100, 0xb000
	s_nop 0
	global_load_lds_dwordx4 v[156:157], off
	s_add_u32 m0, s100, 0xc000
	s_nop 0
	global_load_lds_dwordx4 v[178:179], off
	s_add_u32 m0, s100, 0xd000
	s_nop 0
	global_load_lds_dwordx4 v[180:181], off
	s_add_u32 m0, s100, 0xe000
	s_nop 0
	global_load_lds_dwordx4 v[182:183], off
	s_add_u32 m0, s100, 0xf000
	s_nop 0
	global_load_lds_dwordx4 v[184:185], off
	ds_read_b128 a[0:3], v121
	ds_read_b128 v[80:83], v122
	ds_read_b128 a[4:7], v121 offset:2048
	ds_read_b128 a[8:11], v121 offset:4096
	ds_read_b128 a[12:15], v121 offset:6144
	ds_read_b128 v[92:95], v122 offset:2048
	ds_read_b128 v[88:91], v122 offset:4096
	ds_read_b128 v[84:87], v122 offset:6144
	ds_read_b128 a[16:19], v123
	ds_read_b128 a[20:23], v123 offset:2048
	ds_read_b128 a[24:27], v123 offset:4096
	ds_read_b128 a[28:31], v123 offset:6144
	s_setprio 1
	s_waitcnt lgkmcnt(10)
	v_mfma_f32_16x16x32_bf16 v[0:3], a[0:3], v[80:83], v[0:3]
	s_waitcnt lgkmcnt(9)
	v_mfma_f32_16x16x32_bf16 v[16:19], a[4:7], v[80:83], v[16:19]
	s_waitcnt lgkmcnt(8)
	v_mfma_f32_16x16x32_bf16 v[32:35], a[8:11], v[80:83], v[32:35]
	s_waitcnt lgkmcnt(7)
	v_mfma_f32_16x16x32_bf16 v[48:51], a[12:15], v[80:83], v[48:51]
	ds_read_b128 v[80:83], v124
	s_waitcnt lgkmcnt(7)
	v_mfma_f32_16x16x32_bf16 v[4:7], a[0:3], v[92:95], v[4:7]
	v_lshl_add_u64 v[64:65], 8, 4, v[134:135]
	v_lshl_add_u64 v[66:67], 8, 4, v[152:153]
	v_lshl_add_u64 v[68:69], 8, 4, v[154:155]
	v_mfma_f32_16x16x32_bf16 v[20:23], a[4:7], v[92:95], v[20:23]
	v_lshl_add_u64 v[70:71], 8, 4, v[156:157]
	v_lshl_add_u64 v[76:77], 8, 4, v[178:179]
	v_lshl_add_u64 v[78:79], 8, 4, v[180:181]
	v_mfma_f32_16x16x32_bf16 v[36:39], a[8:11], v[92:95], v[36:39]
	v_lshl_add_u64 v[72:73], 8, 4, v[182:183]
	v_lshl_add_u64 v[74:75], 8, 4, v[184:185]
	v_mfma_f32_16x16x32_bf16 v[52:55], a[12:15], v[92:95], v[52:55]
	ds_read_b128 v[92:95], v124 offset:2048
	s_waitcnt lgkmcnt(7)
	v_mfma_f32_16x16x32_bf16 v[8:11], a[0:3], v[88:91], v[8:11]
	v_mfma_f32_16x16x32_bf16 v[24:27], a[4:7], v[88:91], v[24:27]
	v_mfma_f32_16x16x32_bf16 v[40:43], a[8:11], v[88:91], v[40:43]
	v_mfma_f32_16x16x32_bf16 v[56:59], a[12:15], v[88:91], v[56:59]
	ds_read_b128 v[88:91], v124 offset:4096
	s_waitcnt lgkmcnt(7)
	v_mfma_f32_16x16x32_bf16 v[12:15], a[0:3], v[84:87], v[12:15]
	v_mfma_f32_16x16x32_bf16 v[28:31], a[4:7], v[84:87], v[28:31]
	v_mfma_f32_16x16x32_bf16 v[44:47], a[8:11], v[84:87], v[44:47]
	v_mfma_f32_16x16x32_bf16 v[60:63], a[12:15], v[84:87], v[60:63]
	ds_read_b128 v[84:87], v124 offset:6144
	s_waitcnt lgkmcnt(3)
	v_mfma_f32_16x16x32_bf16 v[0:3], a[16:19], v[80:83], v[0:3]
	v_mfma_f32_16x16x32_bf16 v[16:19], a[20:23], v[80:83], v[16:19]
	v_mfma_f32_16x16x32_bf16 v[32:35], a[24:27], v[80:83], v[32:35]
	v_mfma_f32_16x16x32_bf16 v[48:51], a[28:31], v[80:83], v[48:51]
	s_waitcnt lgkmcnt(2)
	v_mfma_f32_16x16x32_bf16 v[4:7], a[16:19], v[92:95], v[4:7]
	v_mfma_f32_16x16x32_bf16 v[20:23], a[20:23], v[92:95], v[20:23]
	v_mfma_f32_16x16x32_bf16 v[36:39], a[24:27], v[92:95], v[36:39]
	v_mfma_f32_16x16x32_bf16 v[52:55], a[28:31], v[92:95], v[52:55]
	s_waitcnt lgkmcnt(1)
	v_mfma_f32_16x16x32_bf16 v[8:11], a[16:19], v[88:91], v[8:11]
	v_mfma_f32_16x16x32_bf16 v[24:27], a[20:23], v[88:91], v[24:27]
	v_mfma_f32_16x16x32_bf16 v[40:43], a[24:27], v[88:91], v[40:43]
	v_mfma_f32_16x16x32_bf16 v[56:59], a[28:31], v[88:91], v[56:59]
	s_waitcnt lgkmcnt(0)
	v_mfma_f32_16x16x32_bf16 v[12:15], a[16:19], v[84:87], v[12:15]
	v_mfma_f32_16x16x32_bf16 v[28:31], a[20:23], v[84:87], v[28:31]
	v_mfma_f32_16x16x32_bf16 v[44:47], a[24:27], v[84:87], v[44:47]
	v_mfma_f32_16x16x32_bf16 v[60:63], a[28:31], v[84:87], v[60:63]
	s_setprio 0
	s_waitcnt vmcnt(0) lgkmcnt(0)
	s_barrier
	s_add_u32 s34, s34, 0x100
	s_addc_u32 s35, s35, 0
	s_add_u32 m0, s100, 0x0
	s_nop 0
	global_load_lds_dwordx4 v[64:65], off
	s_add_u32 m0, s100, 0x1000
	s_nop 0
	global_load_lds_dwordx4 v[66:67], off
	s_add_u32 m0, s100, 0x2000
	s_nop 0
	global_load_lds_dwordx4 v[68:69], off
	s_add_u32 m0, s100, 0x3000
	s_nop 0
	global_load_lds_dwordx4 v[70:71], off
	s_add_u32 m0, s100, 0x4000
	s_nop 0
	global_load_lds_dwordx4 v[76:77], off
	s_add_u32 m0, s100, 0x5000
	s_nop 0
	global_load_lds_dwordx4 v[78:79], off
	s_add_u32 m0, s100, 0x6000
	s_nop 0
	global_load_lds_dwordx4 v[72:73], off
	s_add_u32 m0, s100, 0x7000
	s_nop 0
	global_load_lds_dwordx4 v[74:75], off
	ds_read_b128 a[0:3], v121 offset:32768
	ds_read_b128 v[80:83], v122 offset:32768
	ds_read_b128 a[4:7], v121 offset:34816
	ds_read_b128 a[8:11], v121 offset:36864
	ds_read_b128 a[12:15], v121 offset:38912
	ds_read_b128 v[92:95], v122 offset:34816
	ds_read_b128 v[88:91], v122 offset:36864
	ds_read_b128 v[84:87], v122 offset:38912
	ds_read_b128 a[16:19], v123 offset:32768
	ds_read_b128 a[20:23], v123 offset:34816
	ds_read_b128 a[24:27], v123 offset:36864
	ds_read_b128 a[28:31], v123 offset:38912
	s_setprio 1
	s_waitcnt lgkmcnt(10)
	v_mfma_f32_16x16x32_bf16 v[0:3], a[0:3], v[80:83], v[0:3]
	s_waitcnt lgkmcnt(9)
	v_mfma_f32_16x16x32_bf16 v[16:19], a[4:7], v[80:83], v[16:19]
	s_waitcnt lgkmcnt(8)
	v_mfma_f32_16x16x32_bf16 v[32:35], a[8:11], v[80:83], v[32:35]
	s_waitcnt lgkmcnt(7)
	v_mfma_f32_16x16x32_bf16 v[48:51], a[12:15], v[80:83], v[48:51]
	ds_read_b128 v[80:83], v124 offset:32768
	s_waitcnt lgkmcnt(7)
	v_mfma_f32_16x16x32_bf16 v[4:7], a[0:3], v[92:95], v[4:7]
	v_lshl_add_u64 v[144:145], v[106:107], 0, s[34:35]
	v_add_co_u32_e32 v134, vcc, s21, v144
	v_lshl_add_u64 v[146:147], v[104:105], 0, s[34:35]
	v_mfma_f32_16x16x32_bf16 v[20:23], a[4:7], v[92:95], v[20:23]
	s_nop 0
	v_addc_co_u32_e32 v135, vcc, 0, v145, vcc
	v_add_co_u32_e32 v152, vcc, s74, v144
	v_mfma_f32_16x16x32_bf16 v[36:39], a[8:11], v[92:95], v[36:39]
	s_mov_b32 s4, 0x38380000
	s_nop 0
	v_addc_co_u32_e32 v153, vcc, 0, v145, vcc
	v_mfma_f32_16x16x32_bf16 v[52:55], a[12:15], v[92:95], v[52:55]
	v_add_co_u32_e32 v154, vcc, s75, v144
	v_addc_co_u32_e32 v155, vcc, 0, v145, vcc
	v_add_co_u32_e32 v156, vcc, s14, v144
	ds_read_b128 v[92:95], v124 offset:34816
	s_waitcnt lgkmcnt(7)
	v_mfma_f32_16x16x32_bf16 v[8:11], a[0:3], v[88:91], v[8:11]
	s_nop 1
	v_addc_co_u32_e32 v157, vcc, 0, v145, vcc
	v_add_co_u32_e32 v178, vcc, s4, v146
	v_mfma_f32_16x16x32_bf16 v[24:27], a[4:7], v[88:91], v[24:27]
	s_mov_b32 s4, 0x383a0000
	s_nop 0
	v_addc_co_u32_e32 v179, vcc, 0, v147, vcc
	v_mfma_f32_16x16x32_bf16 v[40:43], a[8:11], v[88:91], v[40:43]
	v_add_co_u32_e32 v180, vcc, s4, v146
	s_mov_b32 s4, 0x383c0000
	s_nop 0
	v_mfma_f32_16x16x32_bf16 v[56:59], a[12:15], v[88:91], v[56:59]
	v_addc_co_u32_e32 v181, vcc, 0, v147, vcc
	v_add_co_u32_e32 v182, vcc, s4, v146
	s_mov_b32 s4, 0x383e0000
	ds_read_b128 v[88:91], v124 offset:36864
	s_waitcnt lgkmcnt(7)
	v_mfma_f32_16x16x32_bf16 v[12:15], a[0:3], v[84:87], v[12:15]
	s_nop 0
	v_addc_co_u32_e32 v183, vcc, 0, v147, vcc
	v_add_co_u32_e32 v184, vcc, s4, v146
	v_mfma_f32_16x16x32_bf16 v[28:31], a[4:7], v[84:87], v[28:31]
	v_addc_co_u32_e32 v185, vcc, 0, v147, vcc
	v_lshl_add_u64 v[134:135], 8, 4, v[134:135]
	v_lshl_add_u64 v[152:153], 8, 4, v[152:153]
	v_mfma_f32_16x16x32_bf16 v[44:47], a[8:11], v[84:87], v[44:47]
	v_lshl_add_u64 v[154:155], 8, 4, v[154:155]
	v_lshl_add_u64 v[156:157], 8, 4, v[156:157]
	v_lshl_add_u64 v[178:179], 8, 4, v[178:179]
	v_mfma_f32_16x16x32_bf16 v[60:63], a[12:15], v[84:87], v[60:63]
	v_lshl_add_u64 v[180:181], 8, 4, v[180:181]
	v_lshl_add_u64 v[182:183], 8, 4, v[182:183]
	v_lshl_add_u64 v[184:185], 8, 4, v[184:185]
	ds_read_b128 v[84:87], v124 offset:38912
	s_waitcnt lgkmcnt(3)
	v_mfma_f32_16x16x32_bf16 v[0:3], a[16:19], v[80:83], v[0:3]
	v_mfma_f32_16x16x32_bf16 v[16:19], a[20:23], v[80:83], v[16:19]
	v_mfma_f32_16x16x32_bf16 v[32:35], a[24:27], v[80:83], v[32:35]
	v_mfma_f32_16x16x32_bf16 v[48:51], a[28:31], v[80:83], v[48:51]
	s_waitcnt lgkmcnt(2)
	v_mfma_f32_16x16x32_bf16 v[4:7], a[16:19], v[92:95], v[4:7]
	v_mfma_f32_16x16x32_bf16 v[20:23], a[20:23], v[92:95], v[20:23]
	v_mfma_f32_16x16x32_bf16 v[36:39], a[24:27], v[92:95], v[36:39]
	v_mfma_f32_16x16x32_bf16 v[52:55], a[28:31], v[92:95], v[52:55]
	s_waitcnt lgkmcnt(1)
	v_mfma_f32_16x16x32_bf16 v[8:11], a[16:19], v[88:91], v[8:11]
	v_mfma_f32_16x16x32_bf16 v[24:27], a[20:23], v[88:91], v[24:27]
	v_mfma_f32_16x16x32_bf16 v[40:43], a[24:27], v[88:91], v[40:43]
	v_mfma_f32_16x16x32_bf16 v[56:59], a[28:31], v[88:91], v[56:59]
	s_waitcnt lgkmcnt(0)
	v_mfma_f32_16x16x32_bf16 v[12:15], a[16:19], v[84:87], v[12:15]
	v_mfma_f32_16x16x32_bf16 v[28:31], a[20:23], v[84:87], v[28:31]
	v_mfma_f32_16x16x32_bf16 v[44:47], a[24:27], v[84:87], v[44:47]
	v_mfma_f32_16x16x32_bf16 v[60:63], a[28:31], v[84:87], v[60:63]
	s_setprio 0
	s_waitcnt vmcnt(0) lgkmcnt(0)
	s_barrier
	s_cmpk_eq_i32 s34, 0xf00
	s_cbranch_scc0 .LBB0_282
	v_lshl_add_u64 v[64:65], 8, 4, v[64:65]
	v_lshl_add_u64 v[66:67], 8, 4, v[66:67]
	v_lshl_add_u64 v[68:69], 8, 4, v[68:69]
	v_lshl_add_u64 v[70:71], 8, 4, v[70:71]
	v_lshl_add_u64 v[76:77], 8, 4, v[76:77]
	v_lshl_add_u64 v[78:79], 8, 4, v[78:79]
	v_lshl_add_u64 v[72:73], 8, 4, v[72:73]
	v_lshl_add_u64 v[74:75], 8, 4, v[74:75]
	s_add_u32 m0, s100, 0x8000
	s_nop 0
	global_load_lds_dwordx4 v[64:65], off
	s_add_u32 m0, s100, 0x9000
	s_nop 0
	global_load_lds_dwordx4 v[66:67], off
	s_add_u32 m0, s100, 0xa000
	s_nop 0
	global_load_lds_dwordx4 v[68:69], off
	s_add_u32 m0, s100, 0xb000
	s_nop 0
	global_load_lds_dwordx4 v[70:71], off
	s_add_u32 m0, s100, 0xc000
	s_nop 0
	global_load_lds_dwordx4 v[76:77], off
	s_add_u32 m0, s100, 0xd000
	s_nop 0
	global_load_lds_dwordx4 v[78:79], off
	s_add_u32 m0, s100, 0xe000
	s_nop 0
	global_load_lds_dwordx4 v[72:73], off
	s_add_u32 m0, s100, 0xf000
	s_nop 0
	global_load_lds_dwordx4 v[74:75], off
	ds_read_b128 a[0:3], v121
	ds_read_b128 v[80:83], v122
	ds_read_b128 a[4:7], v121 offset:2048
	ds_read_b128 a[8:11], v121 offset:4096
	ds_read_b128 a[12:15], v121 offset:6144
	ds_read_b128 v[92:95], v122 offset:2048
	ds_read_b128 v[88:91], v122 offset:4096
	ds_read_b128 v[84:87], v122 offset:6144
	ds_read_b128 a[16:19], v123
	ds_read_b128 a[20:23], v123 offset:2048
	ds_read_b128 a[24:27], v123 offset:4096
	ds_read_b128 a[28:31], v123 offset:6144
	s_setprio 1
	s_waitcnt lgkmcnt(10)
	v_mfma_f32_16x16x32_bf16 v[0:3], a[0:3], v[80:83], v[0:3]
	s_waitcnt lgkmcnt(9)
	v_mfma_f32_16x16x32_bf16 v[16:19], a[4:7], v[80:83], v[16:19]
	s_waitcnt lgkmcnt(8)
	v_mfma_f32_16x16x32_bf16 v[32:35], a[8:11], v[80:83], v[32:35]
	s_waitcnt lgkmcnt(7)
	v_mfma_f32_16x16x32_bf16 v[48:51], a[12:15], v[80:83], v[48:51]
	ds_read_b128 v[80:83], v124
	s_waitcnt lgkmcnt(7)
	v_mfma_f32_16x16x32_bf16 v[4:7], a[0:3], v[92:95], v[4:7]
	v_mfma_f32_16x16x32_bf16 v[20:23], a[4:7], v[92:95], v[20:23]
	v_mfma_f32_16x16x32_bf16 v[36:39], a[8:11], v[92:95], v[36:39]
	v_mfma_f32_16x16x32_bf16 v[52:55], a[12:15], v[92:95], v[52:55]
	ds_read_b128 v[92:95], v124 offset:2048
	s_waitcnt lgkmcnt(7)
	v_mfma_f32_16x16x32_bf16 v[8:11], a[0:3], v[88:91], v[8:11]
	v_mfma_f32_16x16x32_bf16 v[24:27], a[4:7], v[88:91], v[24:27]
	v_mfma_f32_16x16x32_bf16 v[40:43], a[8:11], v[88:91], v[40:43]
	v_mfma_f32_16x16x32_bf16 v[56:59], a[12:15], v[88:91], v[56:59]
	ds_read_b128 v[88:91], v124 offset:4096
	s_waitcnt lgkmcnt(7)
	v_mfma_f32_16x16x32_bf16 v[12:15], a[0:3], v[84:87], v[12:15]
	v_mfma_f32_16x16x32_bf16 v[28:31], a[4:7], v[84:87], v[28:31]
	v_mfma_f32_16x16x32_bf16 v[44:47], a[8:11], v[84:87], v[44:47]
	v_mfma_f32_16x16x32_bf16 v[60:63], a[12:15], v[84:87], v[60:63]
	ds_read_b128 v[84:87], v124 offset:6144
	s_waitcnt lgkmcnt(3)
	v_mfma_f32_16x16x32_bf16 v[0:3], a[16:19], v[80:83], v[0:3]
	v_mfma_f32_16x16x32_bf16 v[16:19], a[20:23], v[80:83], v[16:19]
	v_mfma_f32_16x16x32_bf16 v[32:35], a[24:27], v[80:83], v[32:35]
	v_mfma_f32_16x16x32_bf16 v[48:51], a[28:31], v[80:83], v[48:51]
	s_waitcnt lgkmcnt(2)
	v_mfma_f32_16x16x32_bf16 v[4:7], a[16:19], v[92:95], v[4:7]
	v_mfma_f32_16x16x32_bf16 v[20:23], a[20:23], v[92:95], v[20:23]
	v_mfma_f32_16x16x32_bf16 v[36:39], a[24:27], v[92:95], v[36:39]
	v_mfma_f32_16x16x32_bf16 v[52:55], a[28:31], v[92:95], v[52:55]
	s_waitcnt lgkmcnt(1)
	v_mfma_f32_16x16x32_bf16 v[8:11], a[16:19], v[88:91], v[8:11]
	v_mfma_f32_16x16x32_bf16 v[24:27], a[20:23], v[88:91], v[24:27]
	v_mfma_f32_16x16x32_bf16 v[40:43], a[24:27], v[88:91], v[40:43]
	v_mfma_f32_16x16x32_bf16 v[56:59], a[28:31], v[88:91], v[56:59]
	s_waitcnt lgkmcnt(0)
	v_mfma_f32_16x16x32_bf16 v[12:15], a[16:19], v[84:87], v[12:15]
	v_mfma_f32_16x16x32_bf16 v[28:31], a[20:23], v[84:87], v[28:31]
	v_mfma_f32_16x16x32_bf16 v[44:47], a[24:27], v[84:87], v[44:47]
	v_mfma_f32_16x16x32_bf16 v[60:63], a[28:31], v[84:87], v[60:63]
	s_setprio 0
	s_waitcnt vmcnt(0) lgkmcnt(0)
	s_barrier
	ds_read_b128 a[0:3], v121 offset:32768
	ds_read_b128 v[80:83], v122 offset:32768
	ds_read_b128 a[4:7], v121 offset:34816
	ds_read_b128 a[8:11], v121 offset:36864
	ds_read_b128 a[12:15], v121 offset:38912
	ds_read_b128 v[92:95], v122 offset:34816
	ds_read_b128 v[88:91], v122 offset:36864
	ds_read_b128 v[84:87], v122 offset:38912
	ds_read_b128 a[16:19], v123 offset:32768
	ds_read_b128 a[20:23], v123 offset:34816
	ds_read_b128 a[24:27], v123 offset:36864
	ds_read_b128 a[28:31], v123 offset:38912
	s_setprio 1
	s_waitcnt lgkmcnt(10)
	v_mfma_f32_16x16x32_bf16 v[0:3], a[0:3], v[80:83], v[0:3]
	s_waitcnt lgkmcnt(9)
	v_mfma_f32_16x16x32_bf16 v[16:19], a[4:7], v[80:83], v[16:19]
	s_waitcnt lgkmcnt(8)
	v_mfma_f32_16x16x32_bf16 v[32:35], a[8:11], v[80:83], v[32:35]
	s_waitcnt lgkmcnt(7)
	v_mfma_f32_16x16x32_bf16 v[48:51], a[12:15], v[80:83], v[48:51]
	ds_read_b128 v[80:83], v124 offset:32768
	s_waitcnt lgkmcnt(7)
	v_mfma_f32_16x16x32_bf16 v[4:7], a[0:3], v[92:95], v[4:7]
	v_mfma_f32_16x16x32_bf16 v[20:23], a[4:7], v[92:95], v[20:23]
	v_mfma_f32_16x16x32_bf16 v[36:39], a[8:11], v[92:95], v[36:39]
	v_mfma_f32_16x16x32_bf16 v[52:55], a[12:15], v[92:95], v[52:55]
	ds_read_b128 v[92:95], v124 offset:34816
	s_waitcnt lgkmcnt(7)
	v_mfma_f32_16x16x32_bf16 v[8:11], a[0:3], v[88:91], v[8:11]
	v_mfma_f32_16x16x32_bf16 v[24:27], a[4:7], v[88:91], v[24:27]
	v_mfma_f32_16x16x32_bf16 v[40:43], a[8:11], v[88:91], v[40:43]
	v_mfma_f32_16x16x32_bf16 v[56:59], a[12:15], v[88:91], v[56:59]
	ds_read_b128 v[88:91], v124 offset:36864
	s_waitcnt lgkmcnt(7)
	v_mfma_f32_16x16x32_bf16 v[12:15], a[0:3], v[84:87], v[12:15]
	v_mfma_f32_16x16x32_bf16 v[28:31], a[4:7], v[84:87], v[28:31]
	v_mfma_f32_16x16x32_bf16 v[44:47], a[8:11], v[84:87], v[44:47]
	v_mfma_f32_16x16x32_bf16 v[60:63], a[12:15], v[84:87], v[60:63]
	ds_read_b128 v[84:87], v124 offset:38912
	s_waitcnt lgkmcnt(3)
	v_mfma_f32_16x16x32_bf16 v[0:3], a[16:19], v[80:83], v[0:3]
	v_mfma_f32_16x16x32_bf16 v[16:19], a[20:23], v[80:83], v[16:19]
	v_mfma_f32_16x16x32_bf16 v[32:35], a[24:27], v[80:83], v[32:35]
	v_mfma_f32_16x16x32_bf16 v[48:51], a[28:31], v[80:83], v[48:51]
	s_waitcnt lgkmcnt(2)
	v_mfma_f32_16x16x32_bf16 v[4:7], a[16:19], v[92:95], v[4:7]
	v_mfma_f32_16x16x32_bf16 v[20:23], a[20:23], v[92:95], v[20:23]
	v_mfma_f32_16x16x32_bf16 v[36:39], a[24:27], v[92:95], v[36:39]
	v_mfma_f32_16x16x32_bf16 v[52:55], a[28:31], v[92:95], v[52:55]
	s_waitcnt lgkmcnt(1)
	v_mfma_f32_16x16x32_bf16 v[8:11], a[16:19], v[88:91], v[8:11]
	v_mfma_f32_16x16x32_bf16 v[24:27], a[20:23], v[88:91], v[24:27]
	v_mfma_f32_16x16x32_bf16 v[40:43], a[24:27], v[88:91], v[40:43]
	v_mfma_f32_16x16x32_bf16 v[56:59], a[28:31], v[88:91], v[56:59]
	s_waitcnt lgkmcnt(0)
	v_mfma_f32_16x16x32_bf16 v[12:15], a[16:19], v[84:87], v[12:15]
	v_mfma_f32_16x16x32_bf16 v[28:31], a[20:23], v[84:87], v[28:31]
	v_mfma_f32_16x16x32_bf16 v[44:47], a[24:27], v[84:87], v[44:47]
	v_mfma_f32_16x16x32_bf16 v[60:63], a[28:31], v[84:87], v[60:63]
	s_setprio 0
	v_readfirstlane_b32 s15, v111
	v_readfirstlane_b32 s4, v110
	s_lshl_b32 s15, s15, 6
	s_waitcnt lgkmcnt(0)
	s_barrier
	s_add_i32 s15, s15, s9
	s_lshl_b32 s23, s4, 6
	s_add_i32 s23, s23, s8
	v_or_b32_e32 v67, s15, v109
	s_movk_i32 s4, 0x800
	s_ashr_i32 s22, s23, 11
	v_cmp_gt_i32_e32 vcc, s4, v67
	v_add_u32_e32 v65, 0x1000, v67
	v_add_u32_e32 v64, v67, v97
	v_lshl_or_b32 v66, s23, 11, v97
	s_and_saveexec_b64 s[8:9], vcc
	v_lshlrev_b32_e32 v90, 2, v64
	v_lshlrev_b32_e32 v91, 2, v65
	s_lshl_b32 s4, s23, 13
	v_add_u32_e32 v92, s4, v90
	s_mov_b32 s4, s23
	s_add_i32 s15, s4, 0xffffe000
	s_lshr_b32 s15, s15, 3
	s_add_i32 s15, s15, 4
	s_cmpk_lt_i32 s4, 0x2000
	s_cselect_b32 s15, s22, s15
	s_mul_i32 s15, s15, 0xc000
	v_add_u32_e32 v89, s15, v91
	global_load_dword v84, v89, s[26:27]
	s_add_i32 s4, s23, 8
	s_add_i32 s15, s4, 0xffffe000
	s_lshr_b32 s15, s15, 3
	s_add_i32 s15, s15, 4
	s_cmpk_lt_i32 s4, 0x2000
	s_cselect_b32 s15, s22, s15
	s_mul_i32 s15, s15, 0xc000
	v_add_u32_e32 v89, s15, v91
	global_load_dword v85, v89, s[26:27]
	s_add_i32 s4, s23, 16
	s_add_i32 s15, s4, 0xffffe000
	s_lshr_b32 s15, s15, 3
	s_add_i32 s15, s15, 4
	s_cmpk_lt_i32 s4, 0x2000
	s_cselect_b32 s15, s22, s15
	s_mul_i32 s15, s15, 0xc000
	v_add_u32_e32 v89, s15, v91
	global_load_dword v86, v89, s[26:27]
	s_add_i32 s4, s23, 24
	s_add_i32 s15, s4, 0xffffe000
	s_lshr_b32 s15, s15, 3
	s_add_i32 s15, s15, 4
	s_cmpk_lt_i32 s4, 0x2000
	s_cselect_b32 s15, s22, s15
	s_mul_i32 s15, s15, 0xc000
	v_add_u32_e32 v89, s15, v91
	global_load_dword v87, v89, s[26:27]
	global_load_dword v68, v92, s[0:1]
	v_add_u32_e32 v88, 0x2000, v92
	global_load_dword v69, v88, s[0:1]
	v_add_u32_e32 v88, 0x4000, v92
	global_load_dword v70, v88, s[0:1]
	v_add_u32_e32 v88, 0x6000, v92
	global_load_dword v71, v88, s[0:1]
	v_add_u32_e32 v88, 0x10000, v92
	global_load_dword v72, v88, s[0:1]
	v_add_u32_e32 v88, 0x12000, v92
	global_load_dword v73, v88, s[0:1]
	v_add_u32_e32 v88, 0x14000, v92
	global_load_dword v74, v88, s[0:1]
	v_add_u32_e32 v88, 0x16000, v92
	global_load_dword v75, v88, s[0:1]
	v_add_u32_e32 v88, 0x20000, v92
	global_load_dword v76, v88, s[0:1]
	v_add_u32_e32 v88, 0x22000, v92
	global_load_dword v77, v88, s[0:1]
	v_add_u32_e32 v88, 0x24000, v92
	global_load_dword v78, v88, s[0:1]
	v_add_u32_e32 v88, 0x26000, v92
	global_load_dword v79, v88, s[0:1]
	v_add_u32_e32 v88, 0x30000, v92
	global_load_dword v80, v88, s[0:1]
	v_add_u32_e32 v88, 0x32000, v92
	global_load_dword v81, v88, s[0:1]
	v_add_u32_e32 v88, 0x34000, v92
	global_load_dword v82, v88, s[0:1]
	v_add_u32_e32 v88, 0x36000, v92
	global_load_dword v83, v88, s[0:1]
	s_mov_b64 exec, s[8:9]
	s_barrier
	v_and_b32_e32 v130, 15, v143
	v_bfe_u32 v131, v143, 4, 2
	v_xor_b32_e32 v131, v131, v130
	v_lshlrev_b32_e32 v131, 4, v131
	v_lshl_add_u32 v131, v130, 8, v131
	v_lshrrev_b32_e32 v130, 6, v143
	v_lshl_add_u32 v131, v130, 14, v131
	ds_write_b128 v131, v[0:3]
	ds_write_b128 v131, v[4:7] offset:4096
	ds_write_b128 v131, v[8:11] offset:8192
	ds_write_b128 v131, v[12:15] offset:12288
	v_xor_b32_e32 v124, 64, v131
	ds_write_b128 v124, v[16:19]
	ds_write_b128 v124, v[20:23] offset:4096
	ds_write_b128 v124, v[24:27] offset:8192
	ds_write_b128 v124, v[28:31] offset:12288
	v_xor_b32_e32 v124, 128, v131
	ds_write_b128 v124, v[32:35]
	ds_write_b128 v124, v[36:39] offset:4096
	ds_write_b128 v124, v[40:43] offset:8192
	ds_write_b128 v124, v[44:47] offset:12288
	v_xor_b32_e32 v124, 192, v131
	ds_write_b128 v124, v[48:51]
	ds_write_b128 v124, v[52:55] offset:4096
	ds_write_b128 v124, v[56:59] offset:8192
	ds_write_b128 v124, v[60:63] offset:12288
	v_and_b32_e32 v121, 31, v143
	v_bfe_u32 v123, v143, 5, 1
	v_and_b32_e32 v131, 15, v121
	v_xor_b32_e32 v123, v123, v131
	v_lshlrev_b32_e32 v123, 4, v123
	v_lshl_add_u32 v123, v121, 8, v123
	v_lshl_add_u32 v123, v130, 14, v123
	ds_read_b128 v[48:51], v123
	ds_read_b128 v[32:35], v123 offset:8192
	v_xor_b32_e32 v122, 32, v123
	ds_read_b128 v[52:55], v122
	ds_read_b128 v[36:39], v122 offset:8192
	v_xor_b32_e32 v122, 64, v123
	ds_read_b128 v[56:59], v122
	ds_read_b128 v[40:43], v122 offset:8192
	v_xor_b32_e32 v122, 96, v123
	ds_read_b128 v[60:63], v122
	ds_read_b128 v[44:47], v122 offset:8192
	v_xor_b32_e32 v122, 128, v123
	ds_read_b128 v[16:19], v122
	ds_read_b128 v[0:3], v122 offset:8192
	v_xor_b32_e32 v122, 160, v123
	ds_read_b128 v[20:23], v122
	ds_read_b128 v[4:7], v122 offset:8192
	v_xor_b32_e32 v122, 192, v123
	ds_read_b128 v[24:27], v122
	ds_read_b128 v[8:11], v122 offset:8192
	v_xor_b32_e32 v122, 224, v123
	ds_read_b128 v[28:31], v122
	ds_read_b128 v[12:15], v122 offset:8192
	s_waitcnt lgkmcnt(0)
	s_barrier
	v_or_b32_e32 v89, 32, v67
	s_movk_i32 s4, 0x800
	v_cmp_gt_i32_e64 s[38:39], s4, v89
	s_mov_b64 s[8:9], exec
	s_and_b64 exec, s[8:9], vcc
	s_waitcnt vmcnt(0)
	v_fma_f32 v48, v48, v84, v68
	v_fma_f32 v49, v49, v84, v69
	v_fma_f32 v50, v50, v84, v70
	v_fma_f32 v51, v51, v84, v71
	v_fma_f32 v52, v52, v85, v72
	v_fma_f32 v53, v53, v85, v73
	v_fma_f32 v54, v54, v85, v74
	v_fma_f32 v55, v55, v85, v75
	v_fma_f32 v56, v56, v86, v76
	v_fma_f32 v57, v57, v86, v77
	v_fma_f32 v58, v58, v86, v78
	v_fma_f32 v59, v59, v86, v79
	v_fma_f32 v60, v60, v87, v80
	v_fma_f32 v61, v61, v87, v81
	v_fma_f32 v62, v62, v87, v82
	v_fma_f32 v63, v63, v87, v83
	s_and_b64 exec, s[8:9], s[38:39]
	v_lshlrev_b32_e32 v90, 2, v64
	v_lshlrev_b32_e32 v91, 2, v65
	v_add_u32_e32 v90, 0x80, v90
	v_add_u32_e32 v91, 0x80, v91
	s_lshl_b32 s4, s23, 13
	v_add_u32_e32 v93, s4, v90
	s_mov_b32 s4, s23
	s_add_i32 s15, s4, 0xffffe000
	s_lshr_b32 s15, s15, 3
	s_add_i32 s15, s15, 4
	s_cmpk_lt_i32 s4, 0x2000
	s_cselect_b32 s15, s22, s15
	s_mul_i32 s15, s15, 0xc000
	v_add_u32_e32 v89, s15, v91
	global_load_dword v84, v89, s[26:27]
	s_add_i32 s4, s23, 8
	s_add_i32 s15, s4, 0xffffe000
	s_lshr_b32 s15, s15, 3
	s_add_i32 s15, s15, 4
	s_cmpk_lt_i32 s4, 0x2000
	s_cselect_b32 s15, s22, s15
	s_mul_i32 s15, s15, 0xc000
	v_add_u32_e32 v89, s15, v91
	global_load_dword v85, v89, s[26:27]
	s_add_i32 s4, s23, 16
	s_add_i32 s15, s4, 0xffffe000
	s_lshr_b32 s15, s15, 3
	s_add_i32 s15, s15, 4
	s_cmpk_lt_i32 s4, 0x2000
	s_cselect_b32 s15, s22, s15
	s_mul_i32 s15, s15, 0xc000
	v_add_u32_e32 v89, s15, v91
	global_load_dword v86, v89, s[26:27]
	s_add_i32 s4, s23, 24
	s_add_i32 s15, s4, 0xffffe000
	s_lshr_b32 s15, s15, 3
	s_add_i32 s15, s15, 4
	s_cmpk_lt_i32 s4, 0x2000
	s_cselect_b32 s15, s22, s15
	s_mul_i32 s15, s15, 0xc000
	v_add_u32_e32 v89, s15, v91
	global_load_dword v87, v89, s[26:27]
	global_load_dword v68, v93, s[0:1]
	v_add_u32_e32 v88, 0x2000, v93
	global_load_dword v69, v88, s[0:1]
	v_add_u32_e32 v88, 0x4000, v93
	global_load_dword v70, v88, s[0:1]
	v_add_u32_e32 v88, 0x6000, v93
	global_load_dword v71, v88, s[0:1]
	v_add_u32_e32 v88, 0x10000, v93
	global_load_dword v72, v88, s[0:1]
	v_add_u32_e32 v88, 0x12000, v93
	global_load_dword v73, v88, s[0:1]
	v_add_u32_e32 v88, 0x14000, v93
	global_load_dword v74, v88, s[0:1]
	v_add_u32_e32 v88, 0x16000, v93
	global_load_dword v75, v88, s[0:1]
	v_add_u32_e32 v88, 0x20000, v93
	global_load_dword v76, v88, s[0:1]
	v_add_u32_e32 v88, 0x22000, v93
	global_load_dword v77, v88, s[0:1]
	v_add_u32_e32 v88, 0x24000, v93
	global_load_dword v78, v88, s[0:1]
	v_add_u32_e32 v88, 0x26000, v93
	global_load_dword v79, v88, s[0:1]
	v_add_u32_e32 v88, 0x30000, v93
	global_load_dword v80, v88, s[0:1]
	v_add_u32_e32 v88, 0x32000, v93
	global_load_dword v81, v88, s[0:1]
	v_add_u32_e32 v88, 0x34000, v93
	global_load_dword v82, v88, s[0:1]
	v_add_u32_e32 v88, 0x36000, v93
	global_load_dword v83, v88, s[0:1]
	s_and_b64 exec, s[8:9], vcc
	global_store_dword v92, v48, s[0:1]
	v_add_u32_e32 v88, 0x2000, v92
	global_store_dword v88, v49, s[0:1]
	v_add_u32_e32 v88, 0x4000, v92
	global_store_dword v88, v50, s[0:1]
	v_add_u32_e32 v88, 0x6000, v92
	global_store_dword v88, v51, s[0:1]
	v_add_u32_e32 v88, 0x10000, v92
	global_store_dword v88, v52, s[0:1]
	v_add_u32_e32 v88, 0x12000, v92
	global_store_dword v88, v53, s[0:1]
	v_add_u32_e32 v88, 0x14000, v92
	global_store_dword v88, v54, s[0:1]
	v_add_u32_e32 v88, 0x16000, v92
	global_store_dword v88, v55, s[0:1]
	v_add_u32_e32 v88, 0x20000, v92
	global_store_dword v88, v56, s[0:1]
	v_add_u32_e32 v88, 0x22000, v92
	global_store_dword v88, v57, s[0:1]
	v_add_u32_e32 v88, 0x24000, v92
	global_store_dword v88, v58, s[0:1]
	v_add_u32_e32 v88, 0x26000, v92
	global_store_dword v88, v59, s[0:1]
	v_add_u32_e32 v88, 0x30000, v92
	global_store_dword v88, v60, s[0:1]
	v_add_u32_e32 v88, 0x32000, v92
	global_store_dword v88, v61, s[0:1]
	v_add_u32_e32 v88, 0x34000, v92
	global_store_dword v88, v62, s[0:1]
	v_add_u32_e32 v88, 0x36000, v92
	global_store_dword v88, v63, s[0:1]
	s_and_b64 exec, s[8:9], s[38:39]
	s_waitcnt vmcnt(16)
	v_fma_f32 v32, v32, v84, v68
	v_fma_f32 v33, v33, v84, v69
	v_fma_f32 v34, v34, v84, v70
	v_fma_f32 v35, v35, v84, v71
	v_fma_f32 v36, v36, v85, v72
	v_fma_f32 v37, v37, v85, v73
	v_fma_f32 v38, v38, v85, v74
	v_fma_f32 v39, v39, v85, v75
	v_fma_f32 v40, v40, v86, v76
	v_fma_f32 v41, v41, v86, v77
	v_fma_f32 v42, v42, v86, v78
	v_fma_f32 v43, v43, v86, v79
	v_fma_f32 v44, v44, v87, v80
	v_fma_f32 v45, v45, v87, v81
	v_fma_f32 v46, v46, v87, v82
	v_fma_f32 v47, v47, v87, v83
	s_and_b64 exec, s[8:9], vcc
	v_lshlrev_b32_e32 v90, 2, v64
	v_lshlrev_b32_e32 v91, 2, v65
	s_lshl_b32 s4, s23, 13
	v_add_u32_e32 v92, s4, v90
	s_add_i32 s4, s23, 32
	s_add_i32 s15, s4, 0xffffe000
	s_lshr_b32 s15, s15, 3
	s_add_i32 s15, s15, 4
	s_cmpk_lt_i32 s4, 0x2000
	s_cselect_b32 s15, s22, s15
	s_mul_i32 s15, s15, 0xc000
	v_add_u32_e32 v89, s15, v91
	global_load_dword v84, v89, s[26:27]
	s_add_i32 s4, s23, 40
	s_add_i32 s15, s4, 0xffffe000
	s_lshr_b32 s15, s15, 3
	s_add_i32 s15, s15, 4
	s_cmpk_lt_i32 s4, 0x2000
	s_cselect_b32 s15, s22, s15
	s_mul_i32 s15, s15, 0xc000
	v_add_u32_e32 v89, s15, v91
	global_load_dword v85, v89, s[26:27]
	s_add_i32 s4, s23, 48
	s_add_i32 s15, s4, 0xffffe000
	s_lshr_b32 s15, s15, 3
	s_add_i32 s15, s15, 4
	s_cmpk_lt_i32 s4, 0x2000
	s_cselect_b32 s15, s22, s15
	s_mul_i32 s15, s15, 0xc000
	v_add_u32_e32 v89, s15, v91
	global_load_dword v86, v89, s[26:27]
	s_add_i32 s4, s23, 56
	s_add_i32 s15, s4, 0xffffe000
	s_lshr_b32 s15, s15, 3
	s_add_i32 s15, s15, 4
	s_cmpk_lt_i32 s4, 0x2000
	s_cselect_b32 s15, s22, s15
	s_mul_i32 s15, s15, 0xc000
	v_add_u32_e32 v89, s15, v91
	global_load_dword v87, v89, s[26:27]
	v_add_u32_e32 v88, 0x40000, v92
	global_load_dword v68, v88, s[0:1]
	v_add_u32_e32 v88, 0x42000, v92
	global_load_dword v69, v88, s[0:1]
	v_add_u32_e32 v88, 0x44000, v92
	global_load_dword v70, v88, s[0:1]
	v_add_u32_e32 v88, 0x46000, v92
	global_load_dword v71, v88, s[0:1]
	v_add_u32_e32 v88, 0x50000, v92
	global_load_dword v72, v88, s[0:1]
	v_add_u32_e32 v88, 0x52000, v92
	global_load_dword v73, v88, s[0:1]
	v_add_u32_e32 v88, 0x54000, v92
	global_load_dword v74, v88, s[0:1]
	v_add_u32_e32 v88, 0x56000, v92
	global_load_dword v75, v88, s[0:1]
	v_add_u32_e32 v88, 0x60000, v92
	global_load_dword v76, v88, s[0:1]
	v_add_u32_e32 v88, 0x62000, v92
	global_load_dword v77, v88, s[0:1]
	v_add_u32_e32 v88, 0x64000, v92
	global_load_dword v78, v88, s[0:1]
	v_add_u32_e32 v88, 0x66000, v92
	global_load_dword v79, v88, s[0:1]
	v_add_u32_e32 v88, 0x70000, v92
	global_load_dword v80, v88, s[0:1]
	v_add_u32_e32 v88, 0x72000, v92
	global_load_dword v81, v88, s[0:1]
	v_add_u32_e32 v88, 0x74000, v92
	global_load_dword v82, v88, s[0:1]
	v_add_u32_e32 v88, 0x76000, v92
	global_load_dword v83, v88, s[0:1]
	s_and_b64 exec, s[8:9], s[38:39]
	global_store_dword v93, v32, s[0:1]
	v_add_u32_e32 v88, 0x2000, v93
	global_store_dword v88, v33, s[0:1]
	v_add_u32_e32 v88, 0x4000, v93
	global_store_dword v88, v34, s[0:1]
	v_add_u32_e32 v88, 0x6000, v93
	global_store_dword v88, v35, s[0:1]
	v_add_u32_e32 v88, 0x10000, v93
	global_store_dword v88, v36, s[0:1]
	v_add_u32_e32 v88, 0x12000, v93
	global_store_dword v88, v37, s[0:1]
	v_add_u32_e32 v88, 0x14000, v93
	global_store_dword v88, v38, s[0:1]
	v_add_u32_e32 v88, 0x16000, v93
	global_store_dword v88, v39, s[0:1]
	v_add_u32_e32 v88, 0x20000, v93
	global_store_dword v88, v40, s[0:1]
	v_add_u32_e32 v88, 0x22000, v93
	global_store_dword v88, v41, s[0:1]
	v_add_u32_e32 v88, 0x24000, v93
	global_store_dword v88, v42, s[0:1]
	v_add_u32_e32 v88, 0x26000, v93
	global_store_dword v88, v43, s[0:1]
	v_add_u32_e32 v88, 0x30000, v93
	global_store_dword v88, v44, s[0:1]
	v_add_u32_e32 v88, 0x32000, v93
	global_store_dword v88, v45, s[0:1]
	v_add_u32_e32 v88, 0x34000, v93
	global_store_dword v88, v46, s[0:1]
	v_add_u32_e32 v88, 0x36000, v93
	global_store_dword v88, v47, s[0:1]
	s_and_b64 exec, s[8:9], vcc
	s_waitcnt vmcnt(16)
	v_fma_f32 v16, v16, v84, v68
	v_fma_f32 v17, v17, v84, v69
	v_fma_f32 v18, v18, v84, v70
	v_fma_f32 v19, v19, v84, v71
	v_fma_f32 v20, v20, v85, v72
	v_fma_f32 v21, v21, v85, v73
	v_fma_f32 v22, v22, v85, v74
	v_fma_f32 v23, v23, v85, v75
	v_fma_f32 v24, v24, v86, v76
	v_fma_f32 v25, v25, v86, v77
	v_fma_f32 v26, v26, v86, v78
	v_fma_f32 v27, v27, v86, v79
	v_fma_f32 v28, v28, v87, v80
	v_fma_f32 v29, v29, v87, v81
	v_fma_f32 v30, v30, v87, v82
	v_fma_f32 v31, v31, v87, v83
	s_and_b64 exec, s[8:9], s[38:39]
	v_lshlrev_b32_e32 v90, 2, v64
	v_lshlrev_b32_e32 v91, 2, v65
	v_add_u32_e32 v90, 0x80, v90
	v_add_u32_e32 v91, 0x80, v91
	s_lshl_b32 s4, s23, 13
	v_add_u32_e32 v93, s4, v90
	s_add_i32 s4, s23, 32
	s_add_i32 s15, s4, 0xffffe000
	s_lshr_b32 s15, s15, 3
	s_add_i32 s15, s15, 4
	s_cmpk_lt_i32 s4, 0x2000
	s_cselect_b32 s15, s22, s15
	s_mul_i32 s15, s15, 0xc000
	v_add_u32_e32 v89, s15, v91
	global_load_dword v84, v89, s[26:27]
	s_add_i32 s4, s23, 40
	s_add_i32 s15, s4, 0xffffe000
	s_lshr_b32 s15, s15, 3
	s_add_i32 s15, s15, 4
	s_cmpk_lt_i32 s4, 0x2000
	s_cselect_b32 s15, s22, s15
	s_mul_i32 s15, s15, 0xc000
	v_add_u32_e32 v89, s15, v91
	global_load_dword v85, v89, s[26:27]
	s_add_i32 s4, s23, 48
	s_add_i32 s15, s4, 0xffffe000
	s_lshr_b32 s15, s15, 3
	s_add_i32 s15, s15, 4
	s_cmpk_lt_i32 s4, 0x2000
	s_cselect_b32 s15, s22, s15
	s_mul_i32 s15, s15, 0xc000
	v_add_u32_e32 v89, s15, v91
	global_load_dword v86, v89, s[26:27]
	s_add_i32 s4, s23, 56
	s_add_i32 s15, s4, 0xffffe000
	s_lshr_b32 s15, s15, 3
	s_add_i32 s15, s15, 4
	s_cmpk_lt_i32 s4, 0x2000
	s_cselect_b32 s15, s22, s15
	s_mul_i32 s15, s15, 0xc000
	v_add_u32_e32 v89, s15, v91
	global_load_dword v87, v89, s[26:27]
	v_add_u32_e32 v88, 0x40000, v93
	global_load_dword v68, v88, s[0:1]
	v_add_u32_e32 v88, 0x42000, v93
	global_load_dword v69, v88, s[0:1]
	v_add_u32_e32 v88, 0x44000, v93
	global_load_dword v70, v88, s[0:1]
	v_add_u32_e32 v88, 0x46000, v93
	global_load_dword v71, v88, s[0:1]
	v_add_u32_e32 v88, 0x50000, v93
	global_load_dword v72, v88, s[0:1]
	v_add_u32_e32 v88, 0x52000, v93
	global_load_dword v73, v88, s[0:1]
	v_add_u32_e32 v88, 0x54000, v93
	global_load_dword v74, v88, s[0:1]
	v_add_u32_e32 v88, 0x56000, v93
	global_load_dword v75, v88, s[0:1]
	v_add_u32_e32 v88, 0x60000, v93
	global_load_dword v76, v88, s[0:1]
	v_add_u32_e32 v88, 0x62000, v93
	global_load_dword v77, v88, s[0:1]
	v_add_u32_e32 v88, 0x64000, v93
	global_load_dword v78, v88, s[0:1]
	v_add_u32_e32 v88, 0x66000, v93
	global_load_dword v79, v88, s[0:1]
	v_add_u32_e32 v88, 0x70000, v93
	global_load_dword v80, v88, s[0:1]
	v_add_u32_e32 v88, 0x72000, v93
	global_load_dword v81, v88, s[0:1]
	v_add_u32_e32 v88, 0x74000, v93
	global_load_dword v82, v88, s[0:1]
	v_add_u32_e32 v88, 0x76000, v93
	global_load_dword v83, v88, s[0:1]
	s_and_b64 exec, s[8:9], vcc
	v_add_u32_e32 v88, 0x40000, v92
	global_store_dword v88, v16, s[0:1]
	v_add_u32_e32 v88, 0x42000, v92
	global_store_dword v88, v17, s[0:1]
	v_add_u32_e32 v88, 0x44000, v92
	global_store_dword v88, v18, s[0:1]
	v_add_u32_e32 v88, 0x46000, v92
	global_store_dword v88, v19, s[0:1]
	v_add_u32_e32 v88, 0x50000, v92
	global_store_dword v88, v20, s[0:1]
	v_add_u32_e32 v88, 0x52000, v92
	global_store_dword v88, v21, s[0:1]
	v_add_u32_e32 v88, 0x54000, v92
	global_store_dword v88, v22, s[0:1]
	v_add_u32_e32 v88, 0x56000, v92
	global_store_dword v88, v23, s[0:1]
	v_add_u32_e32 v88, 0x60000, v92
	global_store_dword v88, v24, s[0:1]
	v_add_u32_e32 v88, 0x62000, v92
	global_store_dword v88, v25, s[0:1]
	v_add_u32_e32 v88, 0x64000, v92
	global_store_dword v88, v26, s[0:1]
	v_add_u32_e32 v88, 0x66000, v92
	global_store_dword v88, v27, s[0:1]
	v_add_u32_e32 v88, 0x70000, v92
	global_store_dword v88, v28, s[0:1]
	v_add_u32_e32 v88, 0x72000, v92
	global_store_dword v88, v29, s[0:1]
	v_add_u32_e32 v88, 0x74000, v92
	global_store_dword v88, v30, s[0:1]
	v_add_u32_e32 v88, 0x76000, v92
	global_store_dword v88, v31, s[0:1]
	s_and_b64 exec, s[8:9], s[38:39]
	s_waitcnt vmcnt(16)
	v_fma_f32 v0, v0, v84, v68
	v_fma_f32 v1, v1, v84, v69
	v_fma_f32 v2, v2, v84, v70
	v_fma_f32 v3, v3, v84, v71
	v_fma_f32 v4, v4, v85, v72
	v_fma_f32 v5, v5, v85, v73
	v_fma_f32 v6, v6, v85, v74
	v_fma_f32 v7, v7, v85, v75
	v_fma_f32 v8, v8, v86, v76
	v_fma_f32 v9, v9, v86, v77
	v_fma_f32 v10, v10, v86, v78
	v_fma_f32 v11, v11, v86, v79
	v_fma_f32 v12, v12, v87, v80
	v_fma_f32 v13, v13, v87, v81
	v_fma_f32 v14, v14, v87, v82
	v_fma_f32 v15, v15, v87, v83
	v_add_u32_e32 v88, 0x40000, v93
	global_store_dword v88, v0, s[0:1]
	v_add_u32_e32 v88, 0x42000, v93
	global_store_dword v88, v1, s[0:1]
	v_add_u32_e32 v88, 0x44000, v93
	global_store_dword v88, v2, s[0:1]
	v_add_u32_e32 v88, 0x46000, v93
	global_store_dword v88, v3, s[0:1]
	v_add_u32_e32 v88, 0x50000, v93
	global_store_dword v88, v4, s[0:1]
	v_add_u32_e32 v88, 0x52000, v93
	global_store_dword v88, v5, s[0:1]
	v_add_u32_e32 v88, 0x54000, v93
	global_store_dword v88, v6, s[0:1]
	v_add_u32_e32 v88, 0x56000, v93
	global_store_dword v88, v7, s[0:1]
	v_add_u32_e32 v88, 0x60000, v93
	global_store_dword v88, v8, s[0:1]
	v_add_u32_e32 v88, 0x62000, v93
	global_store_dword v88, v9, s[0:1]
	v_add_u32_e32 v88, 0x64000, v93
	global_store_dword v88, v10, s[0:1]
	v_add_u32_e32 v88, 0x66000, v93
	global_store_dword v88, v11, s[0:1]
	v_add_u32_e32 v88, 0x70000, v93
	global_store_dword v88, v12, s[0:1]
	v_add_u32_e32 v88, 0x72000, v93
	global_store_dword v88, v13, s[0:1]
	v_add_u32_e32 v88, 0x74000, v93
	global_store_dword v88, v14, s[0:1]
	v_add_u32_e32 v88, 0x76000, v93
	global_store_dword v88, v15, s[0:1]
	s_branch .LBB0_280

.LBB0_970:
	s_add_u32 m0, s100, 0x8000
	s_nop 0
	global_load_lds_dwordx4 v[152:153], off
	s_add_u32 m0, s100, 0x9000
	s_nop 0
	global_load_lds_dwordx4 v[154:155], off
	s_add_u32 m0, s100, 0xa000
	s_nop 0
	global_load_lds_dwordx4 v[156:157], off
	s_add_u32 m0, s100, 0xb000
	s_nop 0
	global_load_lds_dwordx4 v[178:179], off
	s_add_u32 m0, s100, 0xc000
	s_nop 0
	global_load_lds_dwordx4 v[180:181], off
	s_add_u32 m0, s100, 0xd000
	s_nop 0
	global_load_lds_dwordx4 v[182:183], off
	s_add_u32 m0, s100, 0xe000
	s_nop 0
	global_load_lds_dwordx4 v[184:185], off
	s_add_u32 m0, s100, 0xf000
	s_nop 0
	global_load_lds_dwordx4 v[186:187], off
	ds_read_b128 a[0:3], v124
	ds_read_b128 v[80:83], v125
	ds_read_b128 a[4:7], v124 offset:2048
	ds_read_b128 a[8:11], v124 offset:4096
	ds_read_b128 a[12:15], v124 offset:6144
	ds_read_b128 v[92:95], v125 offset:2048
	ds_read_b128 v[88:91], v125 offset:4096
	ds_read_b128 v[84:87], v125 offset:6144
	ds_read_b128 a[16:19], v126
	ds_read_b128 a[20:23], v126 offset:2048
	ds_read_b128 a[24:27], v126 offset:4096
	ds_read_b128 a[28:31], v126 offset:6144
	s_setprio 1
	s_waitcnt lgkmcnt(10)
	v_mfma_f32_16x16x32_bf16 v[0:3], a[0:3], v[80:83], v[0:3]
	s_waitcnt lgkmcnt(9)
	v_mfma_f32_16x16x32_bf16 v[16:19], a[4:7], v[80:83], v[16:19]
	s_waitcnt lgkmcnt(8)
	v_mfma_f32_16x16x32_bf16 v[32:35], a[8:11], v[80:83], v[32:35]
	s_waitcnt lgkmcnt(7)
	v_mfma_f32_16x16x32_bf16 v[48:51], a[12:15], v[80:83], v[48:51]
	ds_read_b128 v[80:83], v127
	s_waitcnt lgkmcnt(7)
	v_mfma_f32_16x16x32_bf16 v[4:7], a[0:3], v[92:95], v[4:7]
	v_lshl_add_u64 v[64:65], 8, 4, v[152:153]
	v_lshl_add_u64 v[66:67], 8, 4, v[154:155]
	v_lshl_add_u64 v[68:69], 8, 4, v[156:157]
	v_mfma_f32_16x16x32_bf16 v[20:23], a[4:7], v[92:95], v[20:23]
	v_lshl_add_u64 v[70:71], 8, 4, v[178:179]
	v_lshl_add_u64 v[76:77], 8, 4, v[180:181]
	v_lshl_add_u64 v[78:79], 8, 4, v[182:183]
	v_mfma_f32_16x16x32_bf16 v[36:39], a[8:11], v[92:95], v[36:39]
	v_lshl_add_u64 v[72:73], 8, 4, v[184:185]
	v_lshl_add_u64 v[74:75], 8, 4, v[186:187]
	v_mfma_f32_16x16x32_bf16 v[52:55], a[12:15], v[92:95], v[52:55]
	ds_read_b128 v[92:95], v127 offset:2048
	s_waitcnt lgkmcnt(7)
	v_mfma_f32_16x16x32_bf16 v[8:11], a[0:3], v[88:91], v[8:11]
	v_mfma_f32_16x16x32_bf16 v[24:27], a[4:7], v[88:91], v[24:27]
	v_mfma_f32_16x16x32_bf16 v[40:43], a[8:11], v[88:91], v[40:43]
	v_mfma_f32_16x16x32_bf16 v[56:59], a[12:15], v[88:91], v[56:59]
	ds_read_b128 v[88:91], v127 offset:4096
	s_waitcnt lgkmcnt(7)
	v_mfma_f32_16x16x32_bf16 v[12:15], a[0:3], v[84:87], v[12:15]
	v_mfma_f32_16x16x32_bf16 v[28:31], a[4:7], v[84:87], v[28:31]
	v_mfma_f32_16x16x32_bf16 v[44:47], a[8:11], v[84:87], v[44:47]
	v_mfma_f32_16x16x32_bf16 v[60:63], a[12:15], v[84:87], v[60:63]
	ds_read_b128 v[84:87], v127 offset:6144
	s_waitcnt lgkmcnt(3)
	v_mfma_f32_16x16x32_bf16 v[0:3], a[16:19], v[80:83], v[0:3]
	v_mfma_f32_16x16x32_bf16 v[16:19], a[20:23], v[80:83], v[16:19]
	v_mfma_f32_16x16x32_bf16 v[32:35], a[24:27], v[80:83], v[32:35]
	v_mfma_f32_16x16x32_bf16 v[48:51], a[28:31], v[80:83], v[48:51]
	s_waitcnt lgkmcnt(2)
	v_mfma_f32_16x16x32_bf16 v[4:7], a[16:19], v[92:95], v[4:7]
	v_mfma_f32_16x16x32_bf16 v[20:23], a[20:23], v[92:95], v[20:23]
	v_mfma_f32_16x16x32_bf16 v[36:39], a[24:27], v[92:95], v[36:39]
	v_mfma_f32_16x16x32_bf16 v[52:55], a[28:31], v[92:95], v[52:55]
	s_waitcnt lgkmcnt(1)
	v_mfma_f32_16x16x32_bf16 v[8:11], a[16:19], v[88:91], v[8:11]
	v_mfma_f32_16x16x32_bf16 v[24:27], a[20:23], v[88:91], v[24:27]
	v_mfma_f32_16x16x32_bf16 v[40:43], a[24:27], v[88:91], v[40:43]
	v_mfma_f32_16x16x32_bf16 v[56:59], a[28:31], v[88:91], v[56:59]
	s_waitcnt lgkmcnt(0)
	v_mfma_f32_16x16x32_bf16 v[12:15], a[16:19], v[84:87], v[12:15]
	v_mfma_f32_16x16x32_bf16 v[28:31], a[20:23], v[84:87], v[28:31]
	v_mfma_f32_16x16x32_bf16 v[44:47], a[24:27], v[84:87], v[44:47]
	v_mfma_f32_16x16x32_bf16 v[60:63], a[28:31], v[84:87], v[60:63]
	s_setprio 0
	s_waitcnt vmcnt(0) lgkmcnt(0)
	s_barrier
	s_add_u32 s36, s36, 0x100
	s_addc_u32 s37, s37, 0
	s_add_u32 m0, s100, 0x0
	s_nop 0
	global_load_lds_dwordx4 v[64:65], off
	s_add_u32 m0, s100, 0x1000
	s_nop 0
	global_load_lds_dwordx4 v[66:67], off
	s_add_u32 m0, s100, 0x2000
	s_nop 0
	global_load_lds_dwordx4 v[68:69], off
	s_add_u32 m0, s100, 0x3000
	s_nop 0
	global_load_lds_dwordx4 v[70:71], off
	s_add_u32 m0, s100, 0x4000
	s_nop 0
	global_load_lds_dwordx4 v[76:77], off
	s_add_u32 m0, s100, 0x5000
	s_nop 0
	global_load_lds_dwordx4 v[78:79], off
	s_add_u32 m0, s100, 0x6000
	s_nop 0
	global_load_lds_dwordx4 v[72:73], off
	s_add_u32 m0, s100, 0x7000
	s_nop 0
	global_load_lds_dwordx4 v[74:75], off
	ds_read_b128 a[0:3], v124 offset:32768
	ds_read_b128 v[80:83], v125 offset:32768
	ds_read_b128 a[4:7], v124 offset:34816
	ds_read_b128 a[8:11], v124 offset:36864
	ds_read_b128 a[12:15], v124 offset:38912
	ds_read_b128 v[92:95], v125 offset:34816
	ds_read_b128 v[88:91], v125 offset:36864
	ds_read_b128 v[84:87], v125 offset:38912
	ds_read_b128 a[16:19], v126 offset:32768
	ds_read_b128 a[20:23], v126 offset:34816
	ds_read_b128 a[24:27], v126 offset:36864
	ds_read_b128 a[28:31], v126 offset:38912
	s_setprio 1
	s_waitcnt lgkmcnt(10)
	v_mfma_f32_16x16x32_bf16 v[0:3], a[0:3], v[80:83], v[0:3]
	s_waitcnt lgkmcnt(9)
	v_mfma_f32_16x16x32_bf16 v[16:19], a[4:7], v[80:83], v[16:19]
	s_waitcnt lgkmcnt(8)
	v_mfma_f32_16x16x32_bf16 v[32:35], a[8:11], v[80:83], v[32:35]
	s_waitcnt lgkmcnt(7)
	v_mfma_f32_16x16x32_bf16 v[48:51], a[12:15], v[80:83], v[48:51]
	ds_read_b128 v[80:83], v127 offset:32768
	s_waitcnt lgkmcnt(7)
	v_mfma_f32_16x16x32_bf16 v[4:7], a[0:3], v[92:95], v[4:7]
	v_lshl_add_u64 v[144:145], v[108:109], 0, s[36:37]
	v_add_co_u32_e32 v152, vcc, s6, v144
	v_lshl_add_u64 v[146:147], v[106:107], 0, s[36:37]
	v_mfma_f32_16x16x32_bf16 v[20:23], a[4:7], v[92:95], v[20:23]
	s_nop 0
	v_addc_co_u32_e32 v153, vcc, 0, v145, vcc
	v_add_co_u32_e32 v154, vcc, s78, v144
	v_mfma_f32_16x16x32_bf16 v[36:39], a[8:11], v[92:95], v[36:39]
	s_nop 1
	v_addc_co_u32_e32 v155, vcc, 0, v145, vcc
	v_add_co_u32_e32 v156, vcc, s63, v144
	v_mfma_f32_16x16x32_bf16 v[52:55], a[12:15], v[92:95], v[52:55]
	v_addc_co_u32_e32 v157, vcc, 0, v145, vcc
	v_add_co_u32_e32 v178, vcc, s7, v144
	s_nop 1
	ds_read_b128 v[92:95], v127 offset:34816
	s_waitcnt lgkmcnt(7)
	v_mfma_f32_16x16x32_bf16 v[8:11], a[0:3], v[88:91], v[8:11]
	v_addc_co_u32_e32 v179, vcc, 0, v145, vcc
	v_add_co_u32_e32 v180, vcc, s79, v146
	v_addc_co_u32_e32 v181, vcc, 0, v147, vcc
	v_mfma_f32_16x16x32_bf16 v[24:27], a[4:7], v[88:91], v[24:27]
	v_add_co_u32_e32 v182, vcc, s82, v146
	s_nop 1
	v_addc_co_u32_e32 v183, vcc, 0, v147, vcc
	v_mfma_f32_16x16x32_bf16 v[40:43], a[8:11], v[88:91], v[40:43]
	v_add_co_u32_e32 v184, vcc, s2, v146
	v_addc_co_u32_e32 v185, vcc, 0, v147, vcc
	v_add_co_u32_e32 v186, vcc, s17, v146
	v_mfma_f32_16x16x32_bf16 v[56:59], a[12:15], v[88:91], v[56:59]
	s_nop 1
	v_addc_co_u32_e32 v187, vcc, 0, v147, vcc
	v_lshl_add_u64 v[152:153], 8, 4, v[152:153]
	ds_read_b128 v[88:91], v127 offset:36864
	s_waitcnt lgkmcnt(7)
	v_mfma_f32_16x16x32_bf16 v[12:15], a[0:3], v[84:87], v[12:15]
	v_lshl_add_u64 v[154:155], 8, 4, v[154:155]
	v_lshl_add_u64 v[156:157], 8, 4, v[156:157]
	v_lshl_add_u64 v[178:179], 8, 4, v[178:179]
	v_mfma_f32_16x16x32_bf16 v[28:31], a[4:7], v[84:87], v[28:31]
	v_lshl_add_u64 v[180:181], 8, 4, v[180:181]
	v_lshl_add_u64 v[182:183], 8, 4, v[182:183]
	v_lshl_add_u64 v[184:185], 8, 4, v[184:185]
	v_mfma_f32_16x16x32_bf16 v[44:47], a[8:11], v[84:87], v[44:47]
	v_lshl_add_u64 v[186:187], 8, 4, v[186:187]
	v_mfma_f32_16x16x32_bf16 v[60:63], a[12:15], v[84:87], v[60:63]
	ds_read_b128 v[84:87], v127 offset:38912
	s_waitcnt lgkmcnt(3)
	v_mfma_f32_16x16x32_bf16 v[0:3], a[16:19], v[80:83], v[0:3]
	v_mfma_f32_16x16x32_bf16 v[16:19], a[20:23], v[80:83], v[16:19]
	v_mfma_f32_16x16x32_bf16 v[32:35], a[24:27], v[80:83], v[32:35]
	v_mfma_f32_16x16x32_bf16 v[48:51], a[28:31], v[80:83], v[48:51]
	s_waitcnt lgkmcnt(2)
	v_mfma_f32_16x16x32_bf16 v[4:7], a[16:19], v[92:95], v[4:7]
	v_mfma_f32_16x16x32_bf16 v[20:23], a[20:23], v[92:95], v[20:23]
	v_mfma_f32_16x16x32_bf16 v[36:39], a[24:27], v[92:95], v[36:39]
	v_mfma_f32_16x16x32_bf16 v[52:55], a[28:31], v[92:95], v[52:55]
	s_waitcnt lgkmcnt(1)
	v_mfma_f32_16x16x32_bf16 v[8:11], a[16:19], v[88:91], v[8:11]
	v_mfma_f32_16x16x32_bf16 v[24:27], a[20:23], v[88:91], v[24:27]
	v_mfma_f32_16x16x32_bf16 v[40:43], a[24:27], v[88:91], v[40:43]
	v_mfma_f32_16x16x32_bf16 v[56:59], a[28:31], v[88:91], v[56:59]
	s_waitcnt lgkmcnt(0)
	v_mfma_f32_16x16x32_bf16 v[12:15], a[16:19], v[84:87], v[12:15]
	v_mfma_f32_16x16x32_bf16 v[28:31], a[20:23], v[84:87], v[28:31]
	v_mfma_f32_16x16x32_bf16 v[44:47], a[24:27], v[84:87], v[44:47]
	v_mfma_f32_16x16x32_bf16 v[60:63], a[28:31], v[84:87], v[60:63]
	s_setprio 0
	s_waitcnt vmcnt(0) lgkmcnt(0)
	s_barrier
	s_cmpk_eq_i32 s36, 0x3f00
	s_cbranch_scc0 .LBB0_970
	v_lshl_add_u64 v[64:65], 8, 4, v[64:65]
	v_lshl_add_u64 v[66:67], 8, 4, v[66:67]
	v_lshl_add_u64 v[68:69], 8, 4, v[68:69]
	v_lshl_add_u64 v[70:71], 8, 4, v[70:71]
	v_lshl_add_u64 v[76:77], 8, 4, v[76:77]
	v_lshl_add_u64 v[78:79], 8, 4, v[78:79]
	v_lshl_add_u64 v[72:73], 8, 4, v[72:73]
	v_lshl_add_u64 v[74:75], 8, 4, v[74:75]
	s_add_u32 m0, s100, 0x8000
	s_nop 0
	global_load_lds_dwordx4 v[64:65], off
	s_add_u32 m0, s100, 0x9000
	s_nop 0
	global_load_lds_dwordx4 v[66:67], off
	s_add_u32 m0, s100, 0xa000
	s_nop 0
	global_load_lds_dwordx4 v[68:69], off
	s_add_u32 m0, s100, 0xb000
	s_nop 0
	global_load_lds_dwordx4 v[70:71], off
	s_add_u32 m0, s100, 0xc000
	s_nop 0
	global_load_lds_dwordx4 v[76:77], off
	s_add_u32 m0, s100, 0xd000
	s_nop 0
	global_load_lds_dwordx4 v[78:79], off
	s_add_u32 m0, s100, 0xe000
	s_nop 0
	global_load_lds_dwordx4 v[72:73], off
	s_add_u32 m0, s100, 0xf000
	s_nop 0
	global_load_lds_dwordx4 v[74:75], off
	ds_read_b128 a[0:3], v124
	ds_read_b128 v[80:83], v125
	ds_read_b128 a[4:7], v124 offset:2048
	ds_read_b128 a[8:11], v124 offset:4096
	ds_read_b128 a[12:15], v124 offset:6144
	ds_read_b128 v[92:95], v125 offset:2048
	ds_read_b128 v[88:91], v125 offset:4096
	ds_read_b128 v[84:87], v125 offset:6144
	ds_read_b128 a[16:19], v126
	ds_read_b128 a[20:23], v126 offset:2048
	ds_read_b128 a[24:27], v126 offset:4096
	ds_read_b128 a[28:31], v126 offset:6144
	s_setprio 1
	s_waitcnt lgkmcnt(10)
	v_mfma_f32_16x16x32_bf16 v[0:3], a[0:3], v[80:83], v[0:3]
	s_waitcnt lgkmcnt(9)
	v_mfma_f32_16x16x32_bf16 v[16:19], a[4:7], v[80:83], v[16:19]
	s_waitcnt lgkmcnt(8)
	v_mfma_f32_16x16x32_bf16 v[32:35], a[8:11], v[80:83], v[32:35]
	s_waitcnt lgkmcnt(7)
	v_mfma_f32_16x16x32_bf16 v[48:51], a[12:15], v[80:83], v[48:51]
	ds_read_b128 v[80:83], v127
	s_waitcnt lgkmcnt(7)
	v_mfma_f32_16x16x32_bf16 v[4:7], a[0:3], v[92:95], v[4:7]
	v_mfma_f32_16x16x32_bf16 v[20:23], a[4:7], v[92:95], v[20:23]
	v_mfma_f32_16x16x32_bf16 v[36:39], a[8:11], v[92:95], v[36:39]
	v_mfma_f32_16x16x32_bf16 v[52:55], a[12:15], v[92:95], v[52:55]
	ds_read_b128 v[92:95], v127 offset:2048
	s_waitcnt lgkmcnt(7)
	v_mfma_f32_16x16x32_bf16 v[8:11], a[0:3], v[88:91], v[8:11]
	v_mfma_f32_16x16x32_bf16 v[24:27], a[4:7], v[88:91], v[24:27]
	v_mfma_f32_16x16x32_bf16 v[40:43], a[8:11], v[88:91], v[40:43]
	v_mfma_f32_16x16x32_bf16 v[56:59], a[12:15], v[88:91], v[56:59]
	ds_read_b128 v[88:91], v127 offset:4096
	s_waitcnt lgkmcnt(7)
	v_mfma_f32_16x16x32_bf16 v[12:15], a[0:3], v[84:87], v[12:15]
	v_mfma_f32_16x16x32_bf16 v[28:31], a[4:7], v[84:87], v[28:31]
	v_mfma_f32_16x16x32_bf16 v[44:47], a[8:11], v[84:87], v[44:47]
	v_mfma_f32_16x16x32_bf16 v[60:63], a[12:15], v[84:87], v[60:63]
	ds_read_b128 v[84:87], v127 offset:6144
	s_waitcnt lgkmcnt(3)
	v_mfma_f32_16x16x32_bf16 v[0:3], a[16:19], v[80:83], v[0:3]
	v_mfma_f32_16x16x32_bf16 v[16:19], a[20:23], v[80:83], v[16:19]
	v_mfma_f32_16x16x32_bf16 v[32:35], a[24:27], v[80:83], v[32:35]
	v_mfma_f32_16x16x32_bf16 v[48:51], a[28:31], v[80:83], v[48:51]
	s_waitcnt lgkmcnt(2)
	v_mfma_f32_16x16x32_bf16 v[4:7], a[16:19], v[92:95], v[4:7]
	v_mfma_f32_16x16x32_bf16 v[20:23], a[20:23], v[92:95], v[20:23]
	v_mfma_f32_16x16x32_bf16 v[36:39], a[24:27], v[92:95], v[36:39]
	v_mfma_f32_16x16x32_bf16 v[52:55], a[28:31], v[92:95], v[52:55]
	s_waitcnt lgkmcnt(1)
	v_mfma_f32_16x16x32_bf16 v[8:11], a[16:19], v[88:91], v[8:11]
	v_mfma_f32_16x16x32_bf16 v[24:27], a[20:23], v[88:91], v[24:27]
	v_mfma_f32_16x16x32_bf16 v[40:43], a[24:27], v[88:91], v[40:43]
	v_mfma_f32_16x16x32_bf16 v[56:59], a[28:31], v[88:91], v[56:59]
	s_waitcnt lgkmcnt(0)
	v_mfma_f32_16x16x32_bf16 v[12:15], a[16:19], v[84:87], v[12:15]
	v_mfma_f32_16x16x32_bf16 v[28:31], a[20:23], v[84:87], v[28:31]
	v_mfma_f32_16x16x32_bf16 v[44:47], a[24:27], v[84:87], v[44:47]
	v_mfma_f32_16x16x32_bf16 v[60:63], a[28:31], v[84:87], v[60:63]
	s_setprio 0
	s_waitcnt vmcnt(0) lgkmcnt(0)
	s_barrier
	ds_read_b128 a[0:3], v124 offset:32768
	ds_read_b128 v[80:83], v125 offset:32768
	ds_read_b128 a[4:7], v124 offset:34816
	ds_read_b128 a[8:11], v124 offset:36864
	ds_read_b128 a[12:15], v124 offset:38912
	ds_read_b128 v[92:95], v125 offset:34816
	ds_read_b128 v[88:91], v125 offset:36864
	ds_read_b128 v[84:87], v125 offset:38912
	ds_read_b128 a[16:19], v126 offset:32768
	ds_read_b128 a[20:23], v126 offset:34816
	ds_read_b128 a[24:27], v126 offset:36864
	ds_read_b128 a[28:31], v126 offset:38912
	s_setprio 1
	s_waitcnt lgkmcnt(10)
	v_mfma_f32_16x16x32_bf16 v[0:3], a[0:3], v[80:83], v[0:3]
	s_waitcnt lgkmcnt(9)
	v_mfma_f32_16x16x32_bf16 v[16:19], a[4:7], v[80:83], v[16:19]
	s_waitcnt lgkmcnt(8)
	v_mfma_f32_16x16x32_bf16 v[32:35], a[8:11], v[80:83], v[32:35]
	s_waitcnt lgkmcnt(7)
	v_mfma_f32_16x16x32_bf16 v[48:51], a[12:15], v[80:83], v[48:51]
	ds_read_b128 v[80:83], v127 offset:32768
	s_waitcnt lgkmcnt(7)
	v_mfma_f32_16x16x32_bf16 v[4:7], a[0:3], v[92:95], v[4:7]
	v_mfma_f32_16x16x32_bf16 v[20:23], a[4:7], v[92:95], v[20:23]
	v_mfma_f32_16x16x32_bf16 v[36:39], a[8:11], v[92:95], v[36:39]
	v_mfma_f32_16x16x32_bf16 v[52:55], a[12:15], v[92:95], v[52:55]
	ds_read_b128 v[92:95], v127 offset:34816
	s_waitcnt lgkmcnt(7)
	v_mfma_f32_16x16x32_bf16 v[8:11], a[0:3], v[88:91], v[8:11]
	v_mfma_f32_16x16x32_bf16 v[24:27], a[4:7], v[88:91], v[24:27]
	v_mfma_f32_16x16x32_bf16 v[40:43], a[8:11], v[88:91], v[40:43]
	v_mfma_f32_16x16x32_bf16 v[56:59], a[12:15], v[88:91], v[56:59]
	ds_read_b128 v[88:91], v127 offset:36864
	s_waitcnt lgkmcnt(7)
	v_mfma_f32_16x16x32_bf16 v[12:15], a[0:3], v[84:87], v[12:15]
	v_mfma_f32_16x16x32_bf16 v[28:31], a[4:7], v[84:87], v[28:31]
	v_mfma_f32_16x16x32_bf16 v[44:47], a[8:11], v[84:87], v[44:47]
	v_mfma_f32_16x16x32_bf16 v[60:63], a[12:15], v[84:87], v[60:63]
	ds_read_b128 v[84:87], v127 offset:38912
	s_waitcnt lgkmcnt(3)
	v_mfma_f32_16x16x32_bf16 v[0:3], a[16:19], v[80:83], v[0:3]
	v_mfma_f32_16x16x32_bf16 v[16:19], a[20:23], v[80:83], v[16:19]
	v_mfma_f32_16x16x32_bf16 v[32:35], a[24:27], v[80:83], v[32:35]
	v_mfma_f32_16x16x32_bf16 v[48:51], a[28:31], v[80:83], v[48:51]
	s_waitcnt lgkmcnt(2)
	v_mfma_f32_16x16x32_bf16 v[4:7], a[16:19], v[92:95], v[4:7]
	v_mfma_f32_16x16x32_bf16 v[20:23], a[20:23], v[92:95], v[20:23]
	v_mfma_f32_16x16x32_bf16 v[36:39], a[24:27], v[92:95], v[36:39]
	v_mfma_f32_16x16x32_bf16 v[52:55], a[28:31], v[92:95], v[52:55]
	s_waitcnt lgkmcnt(1)
	v_mfma_f32_16x16x32_bf16 v[8:11], a[16:19], v[88:91], v[8:11]
	v_mfma_f32_16x16x32_bf16 v[24:27], a[20:23], v[88:91], v[24:27]
	v_mfma_f32_16x16x32_bf16 v[40:43], a[24:27], v[88:91], v[40:43]
	v_mfma_f32_16x16x32_bf16 v[56:59], a[28:31], v[88:91], v[56:59]
	s_waitcnt lgkmcnt(0)
	v_mfma_f32_16x16x32_bf16 v[12:15], a[16:19], v[84:87], v[12:15]
	v_mfma_f32_16x16x32_bf16 v[28:31], a[20:23], v[84:87], v[28:31]
	v_mfma_f32_16x16x32_bf16 v[44:47], a[24:27], v[84:87], v[44:47]
	v_mfma_f32_16x16x32_bf16 v[60:63], a[28:31], v[84:87], v[60:63]
	s_setprio 0
	v_readfirstlane_b32 s15, v113
	v_readfirstlane_b32 s4, v112
	s_lshl_b32 s15, s15, 6
	s_waitcnt lgkmcnt(0)
	s_barrier
	s_add_i32 s15, s15, s9
	s_lshl_b32 s23, s4, 6
	s_add_i32 s23, s23, s8
	v_or_b32_e32 v67, s15, v111
	s_movk_i32 s4, 0x800
	s_ashr_i32 s22, s23, 11
	v_cmp_gt_i32_e32 vcc, s4, v67
	v_add_u32_e32 v65, 0x2800, v67
	v_add_u32_e32 v64, v67, v97
	v_lshl_or_b32 v66, s23, 11, v97
	s_and_saveexec_b64 s[8:9], vcc
	v_lshlrev_b32_e32 v90, 2, v64
	v_lshlrev_b32_e32 v91, 2, v65
	s_lshl_b32 s4, s23, 13
	v_add_u32_e32 v92, s4, v90
	s_mov_b32 s4, s23
	s_add_i32 s15, s4, 0xffffe000
	s_lshr_b32 s15, s15, 3
	s_add_i32 s15, s15, 4
	s_cmpk_lt_i32 s4, 0x2000
	s_cselect_b32 s15, s22, s15
	s_mul_i32 s15, s15, 0xc000
	v_add_u32_e32 v89, s15, v91
	global_load_dword v84, v89, s[26:27]
	s_add_i32 s4, s23, 8
	s_add_i32 s15, s4, 0xffffe000
	s_lshr_b32 s15, s15, 3
	s_add_i32 s15, s15, 4
	s_cmpk_lt_i32 s4, 0x2000
	s_cselect_b32 s15, s22, s15
	s_mul_i32 s15, s15, 0xc000
	v_add_u32_e32 v89, s15, v91
	global_load_dword v85, v89, s[26:27]
	s_add_i32 s4, s23, 16
	s_add_i32 s15, s4, 0xffffe000
	s_lshr_b32 s15, s15, 3
	s_add_i32 s15, s15, 4
	s_cmpk_lt_i32 s4, 0x2000
	s_cselect_b32 s15, s22, s15
	s_mul_i32 s15, s15, 0xc000
	v_add_u32_e32 v89, s15, v91
	global_load_dword v86, v89, s[26:27]
	s_add_i32 s4, s23, 24
	s_add_i32 s15, s4, 0xffffe000
	s_lshr_b32 s15, s15, 3
	s_add_i32 s15, s15, 4
	s_cmpk_lt_i32 s4, 0x2000
	s_cselect_b32 s15, s22, s15
	s_mul_i32 s15, s15, 0xc000
	v_add_u32_e32 v89, s15, v91
	global_load_dword v87, v89, s[26:27]
	global_load_dword v68, v92, s[0:1]
	v_add_u32_e32 v88, 0x2000, v92
	global_load_dword v69, v88, s[0:1]
	v_add_u32_e32 v88, 0x4000, v92
	global_load_dword v70, v88, s[0:1]
	v_add_u32_e32 v88, 0x6000, v92
	global_load_dword v71, v88, s[0:1]
	v_add_u32_e32 v88, 0x10000, v92
	global_load_dword v72, v88, s[0:1]
	v_add_u32_e32 v88, 0x12000, v92
	global_load_dword v73, v88, s[0:1]
	v_add_u32_e32 v88, 0x14000, v92
	global_load_dword v74, v88, s[0:1]
	v_add_u32_e32 v88, 0x16000, v92
	global_load_dword v75, v88, s[0:1]
	v_add_u32_e32 v88, 0x20000, v92
	global_load_dword v76, v88, s[0:1]
	v_add_u32_e32 v88, 0x22000, v92
	global_load_dword v77, v88, s[0:1]
	v_add_u32_e32 v88, 0x24000, v92
	global_load_dword v78, v88, s[0:1]
	v_add_u32_e32 v88, 0x26000, v92
	global_load_dword v79, v88, s[0:1]
	v_add_u32_e32 v88, 0x30000, v92
	global_load_dword v80, v88, s[0:1]
	v_add_u32_e32 v88, 0x32000, v92
	global_load_dword v81, v88, s[0:1]
	v_add_u32_e32 v88, 0x34000, v92
	global_load_dword v82, v88, s[0:1]
	v_add_u32_e32 v88, 0x36000, v92
	global_load_dword v83, v88, s[0:1]
	s_mov_b64 exec, s[8:9]
	s_barrier
	v_and_b32_e32 v132, 15, v143
	v_bfe_u32 v133, v143, 4, 2
	v_xor_b32_e32 v133, v133, v132
	v_lshlrev_b32_e32 v133, 4, v133
	v_lshl_add_u32 v133, v132, 8, v133
	v_lshrrev_b32_e32 v132, 6, v143
	v_lshl_add_u32 v133, v132, 14, v133
	ds_write_b128 v133, v[0:3]
	ds_write_b128 v133, v[4:7] offset:4096
	ds_write_b128 v133, v[8:11] offset:8192
	ds_write_b128 v133, v[12:15] offset:12288
	v_xor_b32_e32 v127, 64, v133
	ds_write_b128 v127, v[16:19]
	ds_write_b128 v127, v[20:23] offset:4096
	ds_write_b128 v127, v[24:27] offset:8192
	ds_write_b128 v127, v[28:31] offset:12288
	v_xor_b32_e32 v127, 128, v133
	ds_write_b128 v127, v[32:35]
	ds_write_b128 v127, v[36:39] offset:4096
	ds_write_b128 v127, v[40:43] offset:8192
	ds_write_b128 v127, v[44:47] offset:12288
	v_xor_b32_e32 v127, 192, v133
	ds_write_b128 v127, v[48:51]
	ds_write_b128 v127, v[52:55] offset:4096
	ds_write_b128 v127, v[56:59] offset:8192
	ds_write_b128 v127, v[60:63] offset:12288
	v_and_b32_e32 v124, 31, v143
	v_bfe_u32 v126, v143, 5, 1
	v_and_b32_e32 v133, 15, v124
	v_xor_b32_e32 v126, v126, v133
	v_lshlrev_b32_e32 v126, 4, v126
	v_lshl_add_u32 v126, v124, 8, v126
	v_lshl_add_u32 v126, v132, 14, v126
	ds_read_b128 v[48:51], v126
	ds_read_b128 v[32:35], v126 offset:8192
	v_xor_b32_e32 v125, 32, v126
	ds_read_b128 v[52:55], v125
	ds_read_b128 v[36:39], v125 offset:8192
	v_xor_b32_e32 v125, 64, v126
	ds_read_b128 v[56:59], v125
	ds_read_b128 v[40:43], v125 offset:8192
	v_xor_b32_e32 v125, 96, v126
	ds_read_b128 v[60:63], v125
	ds_read_b128 v[44:47], v125 offset:8192
	v_xor_b32_e32 v125, 128, v126
	ds_read_b128 v[16:19], v125
	ds_read_b128 v[0:3], v125 offset:8192
	v_xor_b32_e32 v125, 160, v126
	ds_read_b128 v[20:23], v125
	ds_read_b128 v[4:7], v125 offset:8192
	v_xor_b32_e32 v125, 192, v126
	ds_read_b128 v[24:27], v125
	ds_read_b128 v[8:11], v125 offset:8192
	v_xor_b32_e32 v125, 224, v126
	ds_read_b128 v[28:31], v125
	ds_read_b128 v[12:15], v125 offset:8192
	s_waitcnt lgkmcnt(0)
	s_barrier
	v_or_b32_e32 v89, 32, v67
	s_movk_i32 s4, 0x800
	v_cmp_gt_i32_e64 s[38:39], s4, v89
	s_mov_b64 s[8:9], exec
	s_and_b64 exec, s[8:9], vcc
	s_waitcnt vmcnt(0)
	v_fma_f32 v48, v48, v84, v68
	v_fma_f32 v49, v49, v84, v69
	v_fma_f32 v50, v50, v84, v70
	v_fma_f32 v51, v51, v84, v71
	v_fma_f32 v52, v52, v85, v72
	v_fma_f32 v53, v53, v85, v73
	v_fma_f32 v54, v54, v85, v74
	v_fma_f32 v55, v55, v85, v75
	v_fma_f32 v56, v56, v86, v76
	v_fma_f32 v57, v57, v86, v77
	v_fma_f32 v58, v58, v86, v78
	v_fma_f32 v59, v59, v86, v79
	v_fma_f32 v60, v60, v87, v80
	v_fma_f32 v61, v61, v87, v81
	v_fma_f32 v62, v62, v87, v82
	v_fma_f32 v63, v63, v87, v83
	s_and_b64 exec, s[8:9], s[38:39]
	v_lshlrev_b32_e32 v90, 2, v64
	v_lshlrev_b32_e32 v91, 2, v65
	v_add_u32_e32 v90, 0x80, v90
	v_add_u32_e32 v91, 0x80, v91
	s_lshl_b32 s4, s23, 13
	v_add_u32_e32 v93, s4, v90
	s_mov_b32 s4, s23
	s_add_i32 s15, s4, 0xffffe000
	s_lshr_b32 s15, s15, 3
	s_add_i32 s15, s15, 4
	s_cmpk_lt_i32 s4, 0x2000
	s_cselect_b32 s15, s22, s15
	s_mul_i32 s15, s15, 0xc000
	v_add_u32_e32 v89, s15, v91
	global_load_dword v84, v89, s[26:27]
	s_add_i32 s4, s23, 8
	s_add_i32 s15, s4, 0xffffe000
	s_lshr_b32 s15, s15, 3
	s_add_i32 s15, s15, 4
	s_cmpk_lt_i32 s4, 0x2000
	s_cselect_b32 s15, s22, s15
	s_mul_i32 s15, s15, 0xc000
	v_add_u32_e32 v89, s15, v91
	global_load_dword v85, v89, s[26:27]
	s_add_i32 s4, s23, 16
	s_add_i32 s15, s4, 0xffffe000
	s_lshr_b32 s15, s15, 3
	s_add_i32 s15, s15, 4
	s_cmpk_lt_i32 s4, 0x2000
	s_cselect_b32 s15, s22, s15
	s_mul_i32 s15, s15, 0xc000
	v_add_u32_e32 v89, s15, v91
	global_load_dword v86, v89, s[26:27]
	s_add_i32 s4, s23, 24
	s_add_i32 s15, s4, 0xffffe000
	s_lshr_b32 s15, s15, 3
	s_add_i32 s15, s15, 4
	s_cmpk_lt_i32 s4, 0x2000
	s_cselect_b32 s15, s22, s15
	s_mul_i32 s15, s15, 0xc000
	v_add_u32_e32 v89, s15, v91
	global_load_dword v87, v89, s[26:27]
	global_load_dword v68, v93, s[0:1]
	v_add_u32_e32 v88, 0x2000, v93
	global_load_dword v69, v88, s[0:1]
	v_add_u32_e32 v88, 0x4000, v93
	global_load_dword v70, v88, s[0:1]
	v_add_u32_e32 v88, 0x6000, v93
	global_load_dword v71, v88, s[0:1]
	v_add_u32_e32 v88, 0x10000, v93
	global_load_dword v72, v88, s[0:1]
	v_add_u32_e32 v88, 0x12000, v93
	global_load_dword v73, v88, s[0:1]
	v_add_u32_e32 v88, 0x14000, v93
	global_load_dword v74, v88, s[0:1]
	v_add_u32_e32 v88, 0x16000, v93
	global_load_dword v75, v88, s[0:1]
	v_add_u32_e32 v88, 0x20000, v93
	global_load_dword v76, v88, s[0:1]
	v_add_u32_e32 v88, 0x22000, v93
	global_load_dword v77, v88, s[0:1]
	v_add_u32_e32 v88, 0x24000, v93
	global_load_dword v78, v88, s[0:1]
	v_add_u32_e32 v88, 0x26000, v93
	global_load_dword v79, v88, s[0:1]
	v_add_u32_e32 v88, 0x30000, v93
	global_load_dword v80, v88, s[0:1]
	v_add_u32_e32 v88, 0x32000, v93
	global_load_dword v81, v88, s[0:1]
	v_add_u32_e32 v88, 0x34000, v93
	global_load_dword v82, v88, s[0:1]
	v_add_u32_e32 v88, 0x36000, v93
	global_load_dword v83, v88, s[0:1]
	s_and_b64 exec, s[8:9], vcc
	global_store_dword v92, v48, s[0:1]
	v_add_u32_e32 v88, 0x2000, v92
	global_store_dword v88, v49, s[0:1]
	v_add_u32_e32 v88, 0x4000, v92
	global_store_dword v88, v50, s[0:1]
	v_add_u32_e32 v88, 0x6000, v92
	global_store_dword v88, v51, s[0:1]
	v_add_u32_e32 v88, 0x10000, v92
	global_store_dword v88, v52, s[0:1]
	v_add_u32_e32 v88, 0x12000, v92
	global_store_dword v88, v53, s[0:1]
	v_add_u32_e32 v88, 0x14000, v92
	global_store_dword v88, v54, s[0:1]
	v_add_u32_e32 v88, 0x16000, v92
	global_store_dword v88, v55, s[0:1]
	v_add_u32_e32 v88, 0x20000, v92
	global_store_dword v88, v56, s[0:1]
	v_add_u32_e32 v88, 0x22000, v92
	global_store_dword v88, v57, s[0:1]
	v_add_u32_e32 v88, 0x24000, v92
	global_store_dword v88, v58, s[0:1]
	v_add_u32_e32 v88, 0x26000, v92
	global_store_dword v88, v59, s[0:1]
	v_add_u32_e32 v88, 0x30000, v92
	global_store_dword v88, v60, s[0:1]
	v_add_u32_e32 v88, 0x32000, v92
	global_store_dword v88, v61, s[0:1]
	v_add_u32_e32 v88, 0x34000, v92
	global_store_dword v88, v62, s[0:1]
	v_add_u32_e32 v88, 0x36000, v92
	global_store_dword v88, v63, s[0:1]
	s_and_b64 exec, s[8:9], s[38:39]
	s_waitcnt vmcnt(16)
	v_fma_f32 v32, v32, v84, v68
	v_fma_f32 v33, v33, v84, v69
	v_fma_f32 v34, v34, v84, v70
	v_fma_f32 v35, v35, v84, v71
	v_fma_f32 v36, v36, v85, v72
	v_fma_f32 v37, v37, v85, v73
	v_fma_f32 v38, v38, v85, v74
	v_fma_f32 v39, v39, v85, v75
	v_fma_f32 v40, v40, v86, v76
	v_fma_f32 v41, v41, v86, v77
	v_fma_f32 v42, v42, v86, v78
	v_fma_f32 v43, v43, v86, v79
	v_fma_f32 v44, v44, v87, v80
	v_fma_f32 v45, v45, v87, v81
	v_fma_f32 v46, v46, v87, v82
	v_fma_f32 v47, v47, v87, v83
	s_and_b64 exec, s[8:9], vcc
	v_lshlrev_b32_e32 v90, 2, v64
	v_lshlrev_b32_e32 v91, 2, v65
	s_lshl_b32 s4, s23, 13
	v_add_u32_e32 v92, s4, v90
	s_add_i32 s4, s23, 32
	s_add_i32 s15, s4, 0xffffe000
	s_lshr_b32 s15, s15, 3
	s_add_i32 s15, s15, 4
	s_cmpk_lt_i32 s4, 0x2000
	s_cselect_b32 s15, s22, s15
	s_mul_i32 s15, s15, 0xc000
	v_add_u32_e32 v89, s15, v91
	global_load_dword v84, v89, s[26:27]
	s_add_i32 s4, s23, 40
	s_add_i32 s15, s4, 0xffffe000
	s_lshr_b32 s15, s15, 3
	s_add_i32 s15, s15, 4
	s_cmpk_lt_i32 s4, 0x2000
	s_cselect_b32 s15, s22, s15
	s_mul_i32 s15, s15, 0xc000
	v_add_u32_e32 v89, s15, v91
	global_load_dword v85, v89, s[26:27]
	s_add_i32 s4, s23, 48
	s_add_i32 s15, s4, 0xffffe000
	s_lshr_b32 s15, s15, 3
	s_add_i32 s15, s15, 4
	s_cmpk_lt_i32 s4, 0x2000
	s_cselect_b32 s15, s22, s15
	s_mul_i32 s15, s15, 0xc000
	v_add_u32_e32 v89, s15, v91
	global_load_dword v86, v89, s[26:27]
	s_add_i32 s4, s23, 56
	s_add_i32 s15, s4, 0xffffe000
	s_lshr_b32 s15, s15, 3
	s_add_i32 s15, s15, 4
	s_cmpk_lt_i32 s4, 0x2000
	s_cselect_b32 s15, s22, s15
	s_mul_i32 s15, s15, 0xc000
	v_add_u32_e32 v89, s15, v91
	global_load_dword v87, v89, s[26:27]
	v_add_u32_e32 v88, 0x40000, v92
	global_load_dword v68, v88, s[0:1]
	v_add_u32_e32 v88, 0x42000, v92
	global_load_dword v69, v88, s[0:1]
	v_add_u32_e32 v88, 0x44000, v92
	global_load_dword v70, v88, s[0:1]
	v_add_u32_e32 v88, 0x46000, v92
	global_load_dword v71, v88, s[0:1]
	v_add_u32_e32 v88, 0x50000, v92
	global_load_dword v72, v88, s[0:1]
	v_add_u32_e32 v88, 0x52000, v92
	global_load_dword v73, v88, s[0:1]
	v_add_u32_e32 v88, 0x54000, v92
	global_load_dword v74, v88, s[0:1]
	v_add_u32_e32 v88, 0x56000, v92
	global_load_dword v75, v88, s[0:1]
	v_add_u32_e32 v88, 0x60000, v92
	global_load_dword v76, v88, s[0:1]
	v_add_u32_e32 v88, 0x62000, v92
	global_load_dword v77, v88, s[0:1]
	v_add_u32_e32 v88, 0x64000, v92
	global_load_dword v78, v88, s[0:1]
	v_add_u32_e32 v88, 0x66000, v92
	global_load_dword v79, v88, s[0:1]
	v_add_u32_e32 v88, 0x70000, v92
	global_load_dword v80, v88, s[0:1]
	v_add_u32_e32 v88, 0x72000, v92
	global_load_dword v81, v88, s[0:1]
	v_add_u32_e32 v88, 0x74000, v92
	global_load_dword v82, v88, s[0:1]
	v_add_u32_e32 v88, 0x76000, v92
	global_load_dword v83, v88, s[0:1]
	s_and_b64 exec, s[8:9], s[38:39]
	global_store_dword v93, v32, s[0:1]
	v_add_u32_e32 v88, 0x2000, v93
	global_store_dword v88, v33, s[0:1]
	v_add_u32_e32 v88, 0x4000, v93
	global_store_dword v88, v34, s[0:1]
	v_add_u32_e32 v88, 0x6000, v93
	global_store_dword v88, v35, s[0:1]
	v_add_u32_e32 v88, 0x10000, v93
	global_store_dword v88, v36, s[0:1]
	v_add_u32_e32 v88, 0x12000, v93
	global_store_dword v88, v37, s[0:1]
	v_add_u32_e32 v88, 0x14000, v93
	global_store_dword v88, v38, s[0:1]
	v_add_u32_e32 v88, 0x16000, v93
	global_store_dword v88, v39, s[0:1]
	v_add_u32_e32 v88, 0x20000, v93
	global_store_dword v88, v40, s[0:1]
	v_add_u32_e32 v88, 0x22000, v93
	global_store_dword v88, v41, s[0:1]
	v_add_u32_e32 v88, 0x24000, v93
	global_store_dword v88, v42, s[0:1]
	v_add_u32_e32 v88, 0x26000, v93
	global_store_dword v88, v43, s[0:1]
	v_add_u32_e32 v88, 0x30000, v93
	global_store_dword v88, v44, s[0:1]
	v_add_u32_e32 v88, 0x32000, v93
	global_store_dword v88, v45, s[0:1]
	v_add_u32_e32 v88, 0x34000, v93
	global_store_dword v88, v46, s[0:1]
	v_add_u32_e32 v88, 0x36000, v93
	global_store_dword v88, v47, s[0:1]
	s_and_b64 exec, s[8:9], vcc
	s_waitcnt vmcnt(16)
	v_fma_f32 v16, v16, v84, v68
	v_fma_f32 v17, v17, v84, v69
	v_fma_f32 v18, v18, v84, v70
	v_fma_f32 v19, v19, v84, v71
	v_fma_f32 v20, v20, v85, v72
	v_fma_f32 v21, v21, v85, v73
	v_fma_f32 v22, v22, v85, v74
	v_fma_f32 v23, v23, v85, v75
	v_fma_f32 v24, v24, v86, v76
	v_fma_f32 v25, v25, v86, v77
	v_fma_f32 v26, v26, v86, v78
	v_fma_f32 v27, v27, v86, v79
	v_fma_f32 v28, v28, v87, v80
	v_fma_f32 v29, v29, v87, v81
	v_fma_f32 v30, v30, v87, v82
	v_fma_f32 v31, v31, v87, v83
	s_and_b64 exec, s[8:9], s[38:39]
	v_lshlrev_b32_e32 v90, 2, v64
	v_lshlrev_b32_e32 v91, 2, v65
	v_add_u32_e32 v90, 0x80, v90
	v_add_u32_e32 v91, 0x80, v91
	s_lshl_b32 s4, s23, 13
	v_add_u32_e32 v93, s4, v90
	s_add_i32 s4, s23, 32
	s_add_i32 s15, s4, 0xffffe000
	s_lshr_b32 s15, s15, 3
	s_add_i32 s15, s15, 4
	s_cmpk_lt_i32 s4, 0x2000
	s_cselect_b32 s15, s22, s15
	s_mul_i32 s15, s15, 0xc000
	v_add_u32_e32 v89, s15, v91
	global_load_dword v84, v89, s[26:27]
	s_add_i32 s4, s23, 40
	s_add_i32 s15, s4, 0xffffe000
	s_lshr_b32 s15, s15, 3
	s_add_i32 s15, s15, 4
	s_cmpk_lt_i32 s4, 0x2000
	s_cselect_b32 s15, s22, s15
	s_mul_i32 s15, s15, 0xc000
	v_add_u32_e32 v89, s15, v91
	global_load_dword v85, v89, s[26:27]
	s_add_i32 s4, s23, 48
	s_add_i32 s15, s4, 0xffffe000
	s_lshr_b32 s15, s15, 3
	s_add_i32 s15, s15, 4
	s_cmpk_lt_i32 s4, 0x2000
	s_cselect_b32 s15, s22, s15
	s_mul_i32 s15, s15, 0xc000
	v_add_u32_e32 v89, s15, v91
	global_load_dword v86, v89, s[26:27]
	s_add_i32 s4, s23, 56
	s_add_i32 s15, s4, 0xffffe000
	s_lshr_b32 s15, s15, 3
	s_add_i32 s15, s15, 4
	s_cmpk_lt_i32 s4, 0x2000
	s_cselect_b32 s15, s22, s15
	s_mul_i32 s15, s15, 0xc000
	v_add_u32_e32 v89, s15, v91
	global_load_dword v87, v89, s[26:27]
	v_add_u32_e32 v88, 0x40000, v93
	global_load_dword v68, v88, s[0:1]
	v_add_u32_e32 v88, 0x42000, v93
	global_load_dword v69, v88, s[0:1]
	v_add_u32_e32 v88, 0x44000, v93
	global_load_dword v70, v88, s[0:1]
	v_add_u32_e32 v88, 0x46000, v93
	global_load_dword v71, v88, s[0:1]
	v_add_u32_e32 v88, 0x50000, v93
	global_load_dword v72, v88, s[0:1]
	v_add_u32_e32 v88, 0x52000, v93
	global_load_dword v73, v88, s[0:1]
	v_add_u32_e32 v88, 0x54000, v93
	global_load_dword v74, v88, s[0:1]
	v_add_u32_e32 v88, 0x56000, v93
	global_load_dword v75, v88, s[0:1]
	v_add_u32_e32 v88, 0x60000, v93
	global_load_dword v76, v88, s[0:1]
	v_add_u32_e32 v88, 0x62000, v93
	global_load_dword v77, v88, s[0:1]
	v_add_u32_e32 v88, 0x64000, v93
	global_load_dword v78, v88, s[0:1]
	v_add_u32_e32 v88, 0x66000, v93
	global_load_dword v79, v88, s[0:1]
	v_add_u32_e32 v88, 0x70000, v93
	global_load_dword v80, v88, s[0:1]
	v_add_u32_e32 v88, 0x72000, v93
	global_load_dword v81, v88, s[0:1]
	v_add_u32_e32 v88, 0x74000, v93
	global_load_dword v82, v88, s[0:1]
	v_add_u32_e32 v88, 0x76000, v93
	global_load_dword v83, v88, s[0:1]
	s_and_b64 exec, s[8:9], vcc
	v_add_u32_e32 v88, 0x40000, v92
	global_store_dword v88, v16, s[0:1]
	v_add_u32_e32 v88, 0x42000, v92
	global_store_dword v88, v17, s[0:1]
	v_add_u32_e32 v88, 0x44000, v92
	global_store_dword v88, v18, s[0:1]
	v_add_u32_e32 v88, 0x46000, v92
	global_store_dword v88, v19, s[0:1]
	v_add_u32_e32 v88, 0x50000, v92
	global_store_dword v88, v20, s[0:1]
	v_add_u32_e32 v88, 0x52000, v92
	global_store_dword v88, v21, s[0:1]
	v_add_u32_e32 v88, 0x54000, v92
	global_store_dword v88, v22, s[0:1]
	v_add_u32_e32 v88, 0x56000, v92
	global_store_dword v88, v23, s[0:1]
	v_add_u32_e32 v88, 0x60000, v92
	global_store_dword v88, v24, s[0:1]
	v_add_u32_e32 v88, 0x62000, v92
	global_store_dword v88, v25, s[0:1]
	v_add_u32_e32 v88, 0x64000, v92
	global_store_dword v88, v26, s[0:1]
	v_add_u32_e32 v88, 0x66000, v92
	global_store_dword v88, v27, s[0:1]
	v_add_u32_e32 v88, 0x70000, v92
	global_store_dword v88, v28, s[0:1]
	v_add_u32_e32 v88, 0x72000, v92
	global_store_dword v88, v29, s[0:1]
	v_add_u32_e32 v88, 0x74000, v92
	global_store_dword v88, v30, s[0:1]
	v_add_u32_e32 v88, 0x76000, v92
	global_store_dword v88, v31, s[0:1]
	s_and_b64 exec, s[8:9], s[38:39]
	s_waitcnt vmcnt(16)
	v_fma_f32 v0, v0, v84, v68
	v_fma_f32 v1, v1, v84, v69
	v_fma_f32 v2, v2, v84, v70
	v_fma_f32 v3, v3, v84, v71
	v_fma_f32 v4, v4, v85, v72
	v_fma_f32 v5, v5, v85, v73
	v_fma_f32 v6, v6, v85, v74
	v_fma_f32 v7, v7, v85, v75
	v_fma_f32 v8, v8, v86, v76
	v_fma_f32 v9, v9, v86, v77
	v_fma_f32 v10, v10, v86, v78
	v_fma_f32 v11, v11, v86, v79
	v_fma_f32 v12, v12, v87, v80
	v_fma_f32 v13, v13, v87, v81
	v_fma_f32 v14, v14, v87, v82
	v_fma_f32 v15, v15, v87, v83
	v_add_u32_e32 v88, 0x40000, v93
	global_store_dword v88, v0, s[0:1]
	v_add_u32_e32 v88, 0x42000, v93
	global_store_dword v88, v1, s[0:1]
	v_add_u32_e32 v88, 0x44000, v93
	global_store_dword v88, v2, s[0:1]
	v_add_u32_e32 v88, 0x46000, v93
	global_store_dword v88, v3, s[0:1]
	v_add_u32_e32 v88, 0x50000, v93
	global_store_dword v88, v4, s[0:1]
	v_add_u32_e32 v88, 0x52000, v93
	global_store_dword v88, v5, s[0:1]
	v_add_u32_e32 v88, 0x54000, v93
	global_store_dword v88, v6, s[0:1]
	v_add_u32_e32 v88, 0x56000, v93
	global_store_dword v88, v7, s[0:1]
	v_add_u32_e32 v88, 0x60000, v93
	global_store_dword v88, v8, s[0:1]
	v_add_u32_e32 v88, 0x62000, v93
	global_store_dword v88, v9, s[0:1]
	v_add_u32_e32 v88, 0x64000, v93
	global_store_dword v88, v10, s[0:1]
	v_add_u32_e32 v88, 0x66000, v93
	global_store_dword v88, v11, s[0:1]
	v_add_u32_e32 v88, 0x70000, v93
	global_store_dword v88, v12, s[0:1]
	v_add_u32_e32 v88, 0x72000, v93
	global_store_dword v88, v13, s[0:1]
	v_add_u32_e32 v88, 0x74000, v93
	global_store_dword v88, v14, s[0:1]
	v_add_u32_e32 v88, 0x76000, v93
	global_store_dword v88, v15, s[0:1]
	s_branch .LBB0_968
